# residual epilogues of P3/P7/P10 software-pipelined: gate vectors loaded once per row group, 8 x-loads in flight instead of one load-wait-store round trip per 4 columns (same arithmetic)
# speedup vs baseline: 1.0127x; 1.0127x over previous
; __device__ __forceinline__ int fresh_tid() { int t = threadIdx.x; asm volatile("" : "+v"(t)); return t; }
; __device__ __forceinline__ unsigned cvt_pk_bf16(float lo, float hi) { unsigned r; asm volatile("v_cvt_pk_bf16_f32 %0, %1, %2" : "=v"(r) : "v"(lo), "v"(hi)); return r; }
;     __device__ __forceinline__ void operator()(const f32x4 (&acc)[2][2][4][2], const Unit& u, int wr, int wc, int fr_, int fq_) const {
;         (void)fr_; (void)fq_; const int l_ = fresh_tid() & 63, fr = l_ & 15, fq = l_ >> 4;
;         const int col0 = u.pn * BM + wc * 32 + 4 * fq;
;         const bool prm = u.pm < MP / BM;
; #pragma unroll
;         for (int ai = 0; ai < 2; ++ai)
; #pragma unroll
;             for (int m = 0; m < 4; ++m) {
;                 const int rl = ai * HALF + wr * 64 + m * 16 + fr, row = u.pm * BM + rl;
;                 const int b = prm ? (u.pm >> 3) : NB_P + (rl >> 5);
;                 const size_t xoff = (prm ? (size_t)row * D : (size_t)(row - MP) * D) + col0;
;                 const float* gr = gate + (size_t)b * NMOD + col0;
;                 bf16_t* orow = out + (size_t)row * D + col0;
; #pragma unroll
;                 for (int bj = 0; bj < 2; ++bj)
; #pragma unroll
;                     for (int n = 0; n < 2; ++n) { f32x4 xv;
;                         if (IN_F32) xv = *(const f32x4*)((const float*)(prm ? xin_p : xin_s) + xoff + bj * HALF + n * 16);
;                         else { const u32x2 w = *(const u32x2*)((const bf16_t*)(prm ? xin_p : xin_s) + xoff + bj * HALF + n * 16); xv = (f32x4){bflo(w.x), bfhi(w.x), bflo(w.y), bfhi(w.y)}; }
;                         const f32x4 gv = *(const f32x4*)(gr + bj * HALF + n * 16);
;                         const f32x4 r = xv + (gv * coef) * acc[ai][bj][m][n];
;                         u32x2 o; o.x = cvt_pk_bf16(r[0], r[1]); o.y = cvt_pk_bf16(r[2], r[3]); *(u32x2*)(orow + bj * HALF + n * 16) = o; }
;                 asm volatile("" ::: "memory"); }
;     }
.LBB0_619:
	s_and_b64 vcc, exec, s[20:21]
	s_cbranch_vccz .LBB0_621
	v_and_b32_e32 v175, 15, v210
	v_lshrrev_b32_e32 v172, 2, v210
	v_and_b32_e32 v172, 12, v172
	v_or_b32_e32 v172, s76, v172
	s_lshl_b32 s0, s83, 8
	v_or_b32_e32 v172, s0, v172
	v_or_b32_e32 v175, s75, v175
	s_lshl_b32 s0, s1, 8
	v_add_u32_e32 v175, s0, v175
	v_lshlrev_b32_e32 v173, 12, v175
	v_lshl_add_u32 v173, v172, 1, v173
	s_lshr_b32 s15, s75, 5
	s_add_i32 s15, s15, 16
	s_ashr_i32 s0, s1, 3
	s_cmpk_lt_i32 s1, 0x80
	s_cselect_b32 s52, s0, s15
	s_cselect_b32 s53, 0, 1
	s_cselect_b32 s20, s68, s70
	s_cselect_b32 s21, s69, s71
	s_cselect_b32 s0, 0, 0x8000
	v_subrev_u32_e32 v174, s0, v175
	v_lshlrev_b32_e32 v174, 13, v174
	v_lshl_add_u32 v174, v172, 2, v174
	v_lshlrev_b32_e32 v172, 2, v172
	s_mul_i32 s0, s52, 0x12000
	s_add_u32 s22, s63, s0
	s_addc_u32 s23, s72, 0
	global_load_dwordx4 v[184:187], v172, s[22:23]
	global_load_dwordx4 v[188:191], v172, s[22:23] offset:64
	global_load_dwordx4 v[192:195], v172, s[22:23] offset:512
	global_load_dwordx4 v[196:199], v172, s[22:23] offset:576
	v_mov_b32_e32 v178, v174
	v_add_u32_e32 v179, 0x20000, v174
	global_load_dwordx4 v[0:3], v178, s[20:21]
	global_load_dwordx4 v[4:7], v178, s[20:21] offset:64
	global_load_dwordx4 v[8:11], v178, s[20:21] offset:512
	global_load_dwordx4 v[12:15], v178, s[20:21] offset:576
	global_load_dwordx4 v[16:19], v179, s[20:21]
	global_load_dwordx4 v[20:23], v179, s[20:21] offset:64
	global_load_dwordx4 v[24:27], v179, s[20:21] offset:512
	global_load_dwordx4 v[28:31], v179, s[20:21] offset:576
	s_mul_i32 s0, s53, 1
	s_add_i32 s0, s52, s0
	s_mul_i32 s0, s0, 0x12000
	s_add_u32 s34, s63, s0
	s_addc_u32 s35, s72, 0
	global_load_dwordx4 v[200:203], v172, s[34:35]
	global_load_dwordx4 v[204:207], v172, s[34:35] offset:64
	global_load_dwordx4 v[212:215], v172, s[34:35] offset:512
	global_load_dwordx4 v[216:219], v172, s[34:35] offset:576
	v_mov_b32_e32 v176, v173
	v_add_u32_e32 v177, 0x10000, v173
	v_add_u32_e32 v178, 0x40000, v174
	v_add_u32_e32 v179, 0x60000, v174
	s_waitcnt vmcnt(11)
	v_pk_mul_f32 v[184:185], v[184:185], s[12:13] op_sel_hi:[1,0]
	v_pk_mul_f32 v[186:187], v[186:187], s[12:13] op_sel_hi:[1,0]
	v_pk_mul_f32 v[188:189], v[188:189], s[12:13] op_sel_hi:[1,0]
	v_pk_mul_f32 v[190:191], v[190:191], s[12:13] op_sel_hi:[1,0]
	v_pk_mul_f32 v[192:193], v[192:193], s[12:13] op_sel_hi:[1,0]
	v_pk_mul_f32 v[194:195], v[194:195], s[12:13] op_sel_hi:[1,0]
	v_pk_mul_f32 v[196:197], v[196:197], s[12:13] op_sel_hi:[1,0]
	v_pk_mul_f32 v[198:199], v[198:199], s[12:13] op_sel_hi:[1,0]
	v_pk_fma_f32 v[0:1], v[184:185], v[156:157], v[0:1]
	v_pk_fma_f32 v[2:3], v[186:187], v[158:159], v[2:3]
	v_cvt_pk_bf16_f32 v0, v0, v1
	v_cvt_pk_bf16_f32 v1, v2, v3
	global_store_dwordx2 v176, v[0:1], s[24:25]
	global_load_dwordx4 v[0:3], v178, s[20:21]
	s_waitcnt vmcnt(12)
	v_pk_fma_f32 v[4:5], v[188:189], v[152:153], v[4:5]
	v_pk_fma_f32 v[6:7], v[190:191], v[154:155], v[6:7]
	v_cvt_pk_bf16_f32 v4, v4, v5
	v_cvt_pk_bf16_f32 v5, v6, v7
	global_store_dwordx2 v176, v[4:5], s[24:25] offset:32
	global_load_dwordx4 v[4:7], v178, s[20:21] offset:64
	s_waitcnt vmcnt(13)
	v_pk_fma_f32 v[8:9], v[192:193], v[144:145], v[8:9]
	v_pk_fma_f32 v[10:11], v[194:195], v[146:147], v[10:11]
	v_cvt_pk_bf16_f32 v8, v8, v9
	v_cvt_pk_bf16_f32 v9, v10, v11
	global_store_dwordx2 v176, v[8:9], s[24:25] offset:256
	global_load_dwordx4 v[8:11], v178, s[20:21] offset:512
	s_waitcnt vmcnt(14)
	v_pk_fma_f32 v[12:13], v[196:197], v[136:137], v[12:13]
	v_pk_fma_f32 v[14:15], v[198:199], v[138:139], v[14:15]
	v_cvt_pk_bf16_f32 v12, v12, v13
	v_cvt_pk_bf16_f32 v13, v14, v15
	global_store_dwordx2 v176, v[12:13], s[24:25] offset:288
	global_load_dwordx4 v[12:15], v178, s[20:21] offset:576
	s_waitcnt vmcnt(15)
	v_pk_fma_f32 v[16:17], v[184:185], v[148:149], v[16:17]
	v_pk_fma_f32 v[18:19], v[186:187], v[150:151], v[18:19]
	v_cvt_pk_bf16_f32 v16, v16, v17
	v_cvt_pk_bf16_f32 v17, v18, v19
	global_store_dwordx2 v177, v[16:17], s[24:25]
	global_load_dwordx4 v[16:19], v179, s[20:21]
	s_waitcnt vmcnt(16)
	v_pk_fma_f32 v[20:21], v[188:189], v[140:141], v[20:21]
	v_pk_fma_f32 v[22:23], v[190:191], v[142:143], v[22:23]
	v_cvt_pk_bf16_f32 v20, v20, v21
	v_cvt_pk_bf16_f32 v21, v22, v23
	global_store_dwordx2 v177, v[20:21], s[24:25] offset:32
	global_load_dwordx4 v[20:23], v179, s[20:21] offset:64
	s_waitcnt vmcnt(17)
	v_pk_fma_f32 v[24:25], v[192:193], v[132:133], v[24:25]
	v_pk_fma_f32 v[26:27], v[194:195], v[134:135], v[26:27]
	v_cvt_pk_bf16_f32 v24, v24, v25
	v_cvt_pk_bf16_f32 v25, v26, v27
	global_store_dwordx2 v177, v[24:25], s[24:25] offset:256
	global_load_dwordx4 v[24:27], v179, s[20:21] offset:512
	s_waitcnt vmcnt(18)
	v_pk_fma_f32 v[28:29], v[196:197], v[120:121], v[28:29]
	v_pk_fma_f32 v[30:31], v[198:199], v[122:123], v[30:31]
	v_cvt_pk_bf16_f32 v28, v28, v29
	v_cvt_pk_bf16_f32 v29, v30, v31
	global_store_dwordx2 v177, v[28:29], s[24:25] offset:288
	global_load_dwordx4 v[28:31], v179, s[20:21] offset:576
	s_mul_i32 s0, s53, 4
	s_add_i32 s0, s52, s0
	s_mul_i32 s0, s0, 0x12000
	s_add_u32 s22, s63, s0
	s_addc_u32 s23, s72, 0
	global_load_dwordx4 v[184:187], v172, s[22:23]
	global_load_dwordx4 v[188:191], v172, s[22:23] offset:64
	global_load_dwordx4 v[192:195], v172, s[22:23] offset:512
	global_load_dwordx4 v[196:199], v172, s[22:23] offset:576
	v_add_u32_e32 v176, 0x20000, v173
	v_add_u32_e32 v177, 0x30000, v173
	v_add_u32_e32 v178, 0x100000, v174
	v_add_u32_e32 v179, 0x120000, v174
	s_waitcnt vmcnt(18)
; __device__ __forceinline__ int fresh_tid() { int t = threadIdx.x; asm volatile("" : "+v"(t)); return t; }
; __device__ __forceinline__ unsigned cvt_pk_bf16(float lo, float hi) { unsigned r; asm volatile("v_cvt_pk_bf16_f32 %0, %1, %2" : "=v"(r) : "v"(lo), "v"(hi)); return r; }
;     __device__ __forceinline__ void operator()(const f32x4 (&acc)[2][2][4][2], const Unit& u, int wr, int wc, int fr_, int fq_) const {
;         (void)fr_; (void)fq_; const int l_ = fresh_tid() & 63, fr = l_ & 15, fq = l_ >> 4;
;         const int col0 = u.pn * BM + wc * 32 + 4 * fq;
;         const bool prm = u.pm < MP / BM;
; #pragma unroll
;         for (int ai = 0; ai < 2; ++ai)
; #pragma unroll
;             for (int m = 0; m < 4; ++m) {
;                 const int rl = ai * HALF + wr * 64 + m * 16 + fr, row = u.pm * BM + rl;
;                 const int b = prm ? (u.pm >> 3) : NB_P + (rl >> 5);
;                 const size_t xoff = (prm ? (size_t)row * D : (size_t)(row - MP) * D) + col0;
;                 const float* gr = gate + (size_t)b * NMOD + col0;
;                 bf16_t* orow = out + (size_t)row * D + col0;
; #pragma unroll
;                 for (int bj = 0; bj < 2; ++bj)
; #pragma unroll
;                     for (int n = 0; n < 2; ++n) { f32x4 xv;
;                         if (IN_F32) xv = *(const f32x4*)((const float*)(prm ? xin_p : xin_s) + xoff + bj * HALF + n * 16);
;                         else { const u32x2 w = *(const u32x2*)((const bf16_t*)(prm ? xin_p : xin_s) + xoff + bj * HALF + n * 16); xv = (f32x4){bflo(w.x), bfhi(w.x), bflo(w.y), bfhi(w.y)}; }
;                         const f32x4 gv = *(const f32x4*)(gr + bj * HALF + n * 16);
;                         const f32x4 r = xv + (gv * coef) * acc[ai][bj][m][n];
;                         u32x2 o; o.x = cvt_pk_bf16(r[0], r[1]); o.y = cvt_pk_bf16(r[2], r[3]); *(u32x2*)(orow + bj * HALF + n * 16) = o; }
;                 asm volatile("" ::: "memory"); }
;     }
	v_pk_mul_f32 v[200:201], v[200:201], s[12:13] op_sel_hi:[1,0]
	v_pk_mul_f32 v[202:203], v[202:203], s[12:13] op_sel_hi:[1,0]
	v_pk_mul_f32 v[204:205], v[204:205], s[12:13] op_sel_hi:[1,0]
	v_pk_mul_f32 v[206:207], v[206:207], s[12:13] op_sel_hi:[1,0]
	v_pk_mul_f32 v[212:213], v[212:213], s[12:13] op_sel_hi:[1,0]
	v_pk_mul_f32 v[214:215], v[214:215], s[12:13] op_sel_hi:[1,0]
	v_pk_mul_f32 v[216:217], v[216:217], s[12:13] op_sel_hi:[1,0]
	v_pk_mul_f32 v[218:219], v[218:219], s[12:13] op_sel_hi:[1,0]
	v_pk_fma_f32 v[0:1], v[200:201], v[128:129], v[0:1]
	v_pk_fma_f32 v[2:3], v[202:203], v[130:131], v[2:3]
	v_cvt_pk_bf16_f32 v0, v0, v1
	v_cvt_pk_bf16_f32 v1, v2, v3
	global_store_dwordx2 v176, v[0:1], s[24:25]
	global_load_dwordx4 v[0:3], v178, s[20:21]
	s_waitcnt vmcnt(18)
	v_pk_fma_f32 v[4:5], v[204:205], v[124:125], v[4:5]
	v_pk_fma_f32 v[6:7], v[206:207], v[126:127], v[6:7]
	v_cvt_pk_bf16_f32 v4, v4, v5
	v_cvt_pk_bf16_f32 v5, v6, v7
	global_store_dwordx2 v176, v[4:5], s[24:25] offset:32
	global_load_dwordx4 v[4:7], v178, s[20:21] offset:64
	s_waitcnt vmcnt(18)
	v_pk_fma_f32 v[8:9], v[212:213], v[116:117], v[8:9]
	v_pk_fma_f32 v[10:11], v[214:215], v[118:119], v[10:11]
	v_cvt_pk_bf16_f32 v8, v8, v9
	v_cvt_pk_bf16_f32 v9, v10, v11
	global_store_dwordx2 v176, v[8:9], s[24:25] offset:256
	global_load_dwordx4 v[8:11], v178, s[20:21] offset:512
	s_waitcnt vmcnt(18)
	v_pk_fma_f32 v[12:13], v[216:217], v[104:105], v[12:13]
	v_pk_fma_f32 v[14:15], v[218:219], v[106:107], v[14:15]
	v_cvt_pk_bf16_f32 v12, v12, v13
	v_cvt_pk_bf16_f32 v13, v14, v15
	global_store_dwordx2 v176, v[12:13], s[24:25] offset:288
	global_load_dwordx4 v[12:15], v178, s[20:21] offset:576
	s_waitcnt vmcnt(18)
	v_pk_fma_f32 v[16:17], v[200:201], v[112:113], v[16:17]
	v_pk_fma_f32 v[18:19], v[202:203], v[114:115], v[18:19]
	v_cvt_pk_bf16_f32 v16, v16, v17
	v_cvt_pk_bf16_f32 v17, v18, v19
	global_store_dwordx2 v177, v[16:17], s[24:25]
	global_load_dwordx4 v[16:19], v179, s[20:21]
	s_waitcnt vmcnt(18)
	v_pk_fma_f32 v[20:21], v[204:205], v[108:109], v[20:21]
	v_pk_fma_f32 v[22:23], v[206:207], v[110:111], v[22:23]
	v_cvt_pk_bf16_f32 v20, v20, v21
	v_cvt_pk_bf16_f32 v21, v22, v23
	global_store_dwordx2 v177, v[20:21], s[24:25] offset:32
	global_load_dwordx4 v[20:23], v179, s[20:21] offset:64
	s_waitcnt vmcnt(18)
	v_pk_fma_f32 v[24:25], v[212:213], v[100:101], v[24:25]
	v_pk_fma_f32 v[26:27], v[214:215], v[102:103], v[26:27]
	v_cvt_pk_bf16_f32 v24, v24, v25
	v_cvt_pk_bf16_f32 v25, v26, v27
	global_store_dwordx2 v177, v[24:25], s[24:25] offset:256
	global_load_dwordx4 v[24:27], v179, s[20:21] offset:512
	s_waitcnt vmcnt(18)
	v_pk_fma_f32 v[28:29], v[216:217], v[96:97], v[28:29]
	v_pk_fma_f32 v[30:31], v[218:219], v[98:99], v[30:31]
	v_cvt_pk_bf16_f32 v28, v28, v29
	v_cvt_pk_bf16_f32 v29, v30, v31
	global_store_dwordx2 v177, v[28:29], s[24:25] offset:288
	global_load_dwordx4 v[28:31], v179, s[20:21] offset:576
	s_mul_i32 s0, s53, 5
	s_add_i32 s0, s52, s0
	s_mul_i32 s0, s0, 0x12000
	s_add_u32 s34, s63, s0
	s_addc_u32 s35, s72, 0
	global_load_dwordx4 v[200:203], v172, s[34:35]
	global_load_dwordx4 v[204:207], v172, s[34:35] offset:64
	global_load_dwordx4 v[212:215], v172, s[34:35] offset:512
	global_load_dwordx4 v[216:219], v172, s[34:35] offset:576
	v_add_u32_e32 v176, 0x80000, v173
	v_add_u32_e32 v177, 0x90000, v173
	v_add_u32_e32 v178, 0x140000, v174
	v_add_u32_e32 v179, 0x160000, v174
	s_waitcnt vmcnt(18)
	v_pk_mul_f32 v[184:185], v[184:185], s[12:13] op_sel_hi:[1,0]
	v_pk_mul_f32 v[186:187], v[186:187], s[12:13] op_sel_hi:[1,0]
	v_pk_mul_f32 v[188:189], v[188:189], s[12:13] op_sel_hi:[1,0]
	v_pk_mul_f32 v[190:191], v[190:191], s[12:13] op_sel_hi:[1,0]
	v_pk_mul_f32 v[192:193], v[192:193], s[12:13] op_sel_hi:[1,0]
	v_pk_mul_f32 v[194:195], v[194:195], s[12:13] op_sel_hi:[1,0]
	v_pk_mul_f32 v[196:197], v[196:197], s[12:13] op_sel_hi:[1,0]
	v_pk_mul_f32 v[198:199], v[198:199], s[12:13] op_sel_hi:[1,0]
	v_pk_fma_f32 v[0:1], v[184:185], v[92:93], v[0:1]
	v_pk_fma_f32 v[2:3], v[186:187], v[94:95], v[2:3]
	v_cvt_pk_bf16_f32 v0, v0, v1
	v_cvt_pk_bf16_f32 v1, v2, v3
	global_store_dwordx2 v176, v[0:1], s[24:25]
	global_load_dwordx4 v[0:3], v178, s[20:21]
	s_waitcnt vmcnt(18)
	v_pk_fma_f32 v[4:5], v[188:189], v[88:89], v[4:5]
	v_pk_fma_f32 v[6:7], v[190:191], v[90:91], v[6:7]
	v_cvt_pk_bf16_f32 v4, v4, v5
	v_cvt_pk_bf16_f32 v5, v6, v7
	global_store_dwordx2 v176, v[4:5], s[24:25] offset:32
	global_load_dwordx4 v[4:7], v178, s[20:21] offset:64
	s_waitcnt vmcnt(18)
; __device__ __forceinline__ int fresh_tid() { int t = threadIdx.x; asm volatile("" : "+v"(t)); return t; }
; __device__ __forceinline__ unsigned cvt_pk_bf16(float lo, float hi) { unsigned r; asm volatile("v_cvt_pk_bf16_f32 %0, %1, %2" : "=v"(r) : "v"(lo), "v"(hi)); return r; }
;     __device__ __forceinline__ void operator()(const f32x4 (&acc)[2][2][4][2], const Unit& u, int wr, int wc, int fr_, int fq_) const {
;         (void)fr_; (void)fq_; const int l_ = fresh_tid() & 63, fr = l_ & 15, fq = l_ >> 4;
;         const int col0 = u.pn * BM + wc * 32 + 4 * fq;
;         const bool prm = u.pm < MP / BM;
; #pragma unroll
;         for (int ai = 0; ai < 2; ++ai)
; #pragma unroll
;             for (int m = 0; m < 4; ++m) {
;                 const int rl = ai * HALF + wr * 64 + m * 16 + fr, row = u.pm * BM + rl;
;                 const int b = prm ? (u.pm >> 3) : NB_P + (rl >> 5);
;                 const size_t xoff = (prm ? (size_t)row * D : (size_t)(row - MP) * D) + col0;
;                 const float* gr = gate + (size_t)b * NMOD + col0;
;                 bf16_t* orow = out + (size_t)row * D + col0;
; #pragma unroll
;                 for (int bj = 0; bj < 2; ++bj)
; #pragma unroll
;                     for (int n = 0; n < 2; ++n) { f32x4 xv;
;                         if (IN_F32) xv = *(const f32x4*)((const float*)(prm ? xin_p : xin_s) + xoff + bj * HALF + n * 16);
;                         else { const u32x2 w = *(const u32x2*)((const bf16_t*)(prm ? xin_p : xin_s) + xoff + bj * HALF + n * 16); xv = (f32x4){bflo(w.x), bfhi(w.x), bflo(w.y), bfhi(w.y)}; }
;                         const f32x4 gv = *(const f32x4*)(gr + bj * HALF + n * 16);
;                         const f32x4 r = xv + (gv * coef) * acc[ai][bj][m][n];
;                         u32x2 o; o.x = cvt_pk_bf16(r[0], r[1]); o.y = cvt_pk_bf16(r[2], r[3]); *(u32x2*)(orow + bj * HALF + n * 16) = o; }
;                 asm volatile("" ::: "memory"); }
;     }
	v_pk_fma_f32 v[8:9], v[192:193], v[84:85], v[8:9]
	v_pk_fma_f32 v[10:11], v[194:195], v[86:87], v[10:11]
	v_cvt_pk_bf16_f32 v8, v8, v9
	v_cvt_pk_bf16_f32 v9, v10, v11
	global_store_dwordx2 v176, v[8:9], s[24:25] offset:256
	global_load_dwordx4 v[8:11], v178, s[20:21] offset:512
	s_waitcnt vmcnt(18)
	v_pk_fma_f32 v[12:13], v[196:197], v[72:73], v[12:13]
	v_pk_fma_f32 v[14:15], v[198:199], v[74:75], v[14:15]
	v_cvt_pk_bf16_f32 v12, v12, v13
	v_cvt_pk_bf16_f32 v13, v14, v15
	global_store_dwordx2 v176, v[12:13], s[24:25] offset:288
	global_load_dwordx4 v[12:15], v178, s[20:21] offset:576
	s_waitcnt vmcnt(18)
	v_pk_fma_f32 v[16:17], v[184:185], v[80:81], v[16:17]
	v_pk_fma_f32 v[18:19], v[186:187], v[82:83], v[18:19]
	v_cvt_pk_bf16_f32 v16, v16, v17
	v_cvt_pk_bf16_f32 v17, v18, v19
	global_store_dwordx2 v177, v[16:17], s[24:25]
	global_load_dwordx4 v[16:19], v179, s[20:21]
	s_waitcnt vmcnt(18)
	v_pk_fma_f32 v[20:21], v[188:189], v[76:77], v[20:21]
	v_pk_fma_f32 v[22:23], v[190:191], v[78:79], v[22:23]
	v_cvt_pk_bf16_f32 v20, v20, v21
	v_cvt_pk_bf16_f32 v21, v22, v23
	global_store_dwordx2 v177, v[20:21], s[24:25] offset:32
	global_load_dwordx4 v[20:23], v179, s[20:21] offset:64
	s_waitcnt vmcnt(18)
	v_pk_fma_f32 v[24:25], v[192:193], v[68:69], v[24:25]
	v_pk_fma_f32 v[26:27], v[194:195], v[70:71], v[26:27]
	v_cvt_pk_bf16_f32 v24, v24, v25
	v_cvt_pk_bf16_f32 v25, v26, v27
	global_store_dwordx2 v177, v[24:25], s[24:25] offset:256
	global_load_dwordx4 v[24:27], v179, s[20:21] offset:512
	s_waitcnt vmcnt(18)
	v_pk_fma_f32 v[28:29], v[196:197], v[56:57], v[28:29]
	v_pk_fma_f32 v[30:31], v[198:199], v[58:59], v[30:31]
	v_cvt_pk_bf16_f32 v28, v28, v29
	v_cvt_pk_bf16_f32 v29, v30, v31
	global_store_dwordx2 v177, v[28:29], s[24:25] offset:288
	global_load_dwordx4 v[28:31], v179, s[20:21] offset:576
	v_add_u32_e32 v176, 0xa0000, v173
	v_add_u32_e32 v177, 0xb0000, v173
	s_waitcnt vmcnt(14)
	v_pk_mul_f32 v[200:201], v[200:201], s[12:13] op_sel_hi:[1,0]
	v_pk_mul_f32 v[202:203], v[202:203], s[12:13] op_sel_hi:[1,0]
	v_pk_mul_f32 v[204:205], v[204:205], s[12:13] op_sel_hi:[1,0]
	v_pk_mul_f32 v[206:207], v[206:207], s[12:13] op_sel_hi:[1,0]
	v_pk_mul_f32 v[212:213], v[212:213], s[12:13] op_sel_hi:[1,0]
	v_pk_mul_f32 v[214:215], v[214:215], s[12:13] op_sel_hi:[1,0]
	v_pk_mul_f32 v[216:217], v[216:217], s[12:13] op_sel_hi:[1,0]
	v_pk_mul_f32 v[218:219], v[218:219], s[12:13] op_sel_hi:[1,0]
	v_pk_fma_f32 v[0:1], v[200:201], v[64:65], v[0:1]
	v_pk_fma_f32 v[2:3], v[202:203], v[66:67], v[2:3]
	v_cvt_pk_bf16_f32 v0, v0, v1
	v_cvt_pk_bf16_f32 v1, v2, v3
	global_store_dwordx2 v176, v[0:1], s[24:25]
	s_waitcnt vmcnt(13)
	v_pk_fma_f32 v[4:5], v[204:205], v[60:61], v[4:5]
	v_pk_fma_f32 v[6:7], v[206:207], v[62:63], v[6:7]
	v_cvt_pk_bf16_f32 v4, v4, v5
	v_cvt_pk_bf16_f32 v5, v6, v7
	global_store_dwordx2 v176, v[4:5], s[24:25] offset:32
	s_waitcnt vmcnt(12)
	v_pk_fma_f32 v[8:9], v[212:213], v[52:53], v[8:9]
	v_pk_fma_f32 v[10:11], v[214:215], v[54:55], v[10:11]
	v_cvt_pk_bf16_f32 v8, v8, v9
	v_cvt_pk_bf16_f32 v9, v10, v11
	global_store_dwordx2 v176, v[8:9], s[24:25] offset:256
	s_waitcnt vmcnt(11)
	v_pk_fma_f32 v[12:13], v[216:217], v[40:41], v[12:13]
	v_pk_fma_f32 v[14:15], v[218:219], v[42:43], v[14:15]
	v_cvt_pk_bf16_f32 v12, v12, v13
	v_cvt_pk_bf16_f32 v13, v14, v15
	global_store_dwordx2 v176, v[12:13], s[24:25] offset:288
	s_waitcnt vmcnt(10)
	v_pk_fma_f32 v[16:17], v[200:201], v[48:49], v[16:17]
	v_pk_fma_f32 v[18:19], v[202:203], v[50:51], v[18:19]
	v_cvt_pk_bf16_f32 v16, v16, v17
	v_cvt_pk_bf16_f32 v17, v18, v19
	global_store_dwordx2 v177, v[16:17], s[24:25]
	s_waitcnt vmcnt(9)
	v_pk_fma_f32 v[20:21], v[204:205], v[44:45], v[20:21]
	v_pk_fma_f32 v[22:23], v[206:207], v[46:47], v[22:23]
	v_cvt_pk_bf16_f32 v20, v20, v21
	v_cvt_pk_bf16_f32 v21, v22, v23
	global_store_dwordx2 v177, v[20:21], s[24:25] offset:32
	s_waitcnt vmcnt(8)
	v_pk_fma_f32 v[24:25], v[212:213], v[36:37], v[24:25]
	v_pk_fma_f32 v[26:27], v[214:215], v[38:39], v[26:27]
	v_cvt_pk_bf16_f32 v24, v24, v25
	v_cvt_pk_bf16_f32 v25, v26, v27
	global_store_dwordx2 v177, v[24:25], s[24:25] offset:256
	s_waitcnt vmcnt(7)
	v_pk_fma_f32 v[28:29], v[216:217], v[32:33], v[28:29]
	v_pk_fma_f32 v[30:31], v[218:219], v[34:35], v[30:31]
	v_cvt_pk_bf16_f32 v28, v28, v29
	v_cvt_pk_bf16_f32 v29, v30, v31
	global_store_dwordx2 v177, v[28:29], s[24:25] offset:288

; __device__ __forceinline__ int fresh_tid() { int t = threadIdx.x; asm volatile("" : "+v"(t)); return t; }
; __device__ __forceinline__ unsigned cvt_pk_bf16(float lo, float hi) { unsigned r; asm volatile("v_cvt_pk_bf16_f32 %0, %1, %2" : "=v"(r) : "v"(lo), "v"(hi)); return r; }
;     __device__ __forceinline__ void operator()(const f32x4 (&acc)[2][2][4][2], const Unit& u, int wr, int wc, int fr_, int fq_) const {
;         (void)fr_; (void)fq_; const int l_ = fresh_tid() & 63, fr = l_ & 15, fq = l_ >> 4;
;         const int col0 = u.pn * BM + wc * 32 + 4 * fq;
;         const bool prm = u.pm < MP / BM;
; #pragma unroll
;         for (int ai = 0; ai < 2; ++ai)
; #pragma unroll
;             for (int m = 0; m < 4; ++m) {
;                 const int rl = ai * HALF + wr * 64 + m * 16 + fr, row = u.pm * BM + rl;
;                 const int b = prm ? (u.pm >> 3) : NB_P + (rl >> 5);
;                 const size_t xoff = (prm ? (size_t)row * D : (size_t)(row - MP) * D) + col0;
;                 const float* gr = gate + (size_t)b * NMOD + col0;
;                 bf16_t* orow = out + (size_t)row * D + col0;
; #pragma unroll
;                 for (int bj = 0; bj < 2; ++bj)
; #pragma unroll
;                     for (int n = 0; n < 2; ++n) { f32x4 xv;
;                         if (IN_F32) xv = *(const f32x4*)((const float*)(prm ? xin_p : xin_s) + xoff + bj * HALF + n * 16);
;                         else { const u32x2 w = *(const u32x2*)((const bf16_t*)(prm ? xin_p : xin_s) + xoff + bj * HALF + n * 16); xv = (f32x4){bflo(w.x), bfhi(w.x), bflo(w.y), bfhi(w.y)}; }
;                         const f32x4 gv = *(const f32x4*)(gr + bj * HALF + n * 16);
;                         const f32x4 r = xv + (gv * coef) * acc[ai][bj][m][n];
;                         u32x2 o; o.x = cvt_pk_bf16(r[0], r[1]); o.y = cvt_pk_bf16(r[2], r[3]); *(u32x2*)(orow + bj * HALF + n * 16) = o; }
;                 asm volatile("" ::: "memory"); }
;     }
.LBB0_1077:
	s_and_b64 vcc, exec, s[38:39]
	s_cbranch_vccz .LBB0_1079
	v_and_b32_e32 v142, 15, v210
	v_lshrrev_b32_e32 v140, 2, v210
	v_and_b32_e32 v140, 12, v140
	v_or_b32_e32 v140, s61, v140
	s_lshl_b32 s11, s36, 8
	v_or_b32_e32 v140, s11, v140
	v_or_b32_e32 v142, s60, v142
	s_lshl_b32 s11, s34, 8
	v_add_u32_e32 v142, s11, v142
	v_lshlrev_b32_e32 v141, 12, v142
	v_lshl_add_u32 v141, v140, 1, v141
	s_lshr_b32 s13, s60, 5
	s_add_i32 s13, s13, 16
	s_ashr_i32 s11, s34, 3
	s_cmpk_lt_i32 s34, 0x80
	s_cselect_b32 s15, s11, s13
	s_cselect_b32 s20, 0, 1
	v_lshlrev_b32_e32 v140, 2, v140
	s_mul_i32 s11, s15, 0x12000
	s_add_u32 s38, s56, s11
	s_addc_u32 s39, s57, 0
	global_load_dwordx4 v[180:183], v140, s[38:39]
	global_load_dwordx4 v[184:187], v140, s[38:39] offset:64
	global_load_dwordx4 v[188:191], v140, s[38:39] offset:512
	global_load_dwordx4 v[192:195], v140, s[38:39] offset:576
	v_mov_b32_e32 v208, v141
	v_add_u32_e32 v209, 0x10000, v141
	global_load_dwordx2 v[150:151], v208, s[24:25]
	global_load_dwordx2 v[154:155], v208, s[24:25] offset:32
	global_load_dwordx2 v[158:159], v208, s[24:25] offset:256
	global_load_dwordx2 v[162:163], v208, s[24:25] offset:288
	global_load_dwordx2 v[166:167], v209, s[24:25]
	global_load_dwordx2 v[170:171], v209, s[24:25] offset:32
	global_load_dwordx2 v[174:175], v209, s[24:25] offset:256
	global_load_dwordx2 v[178:179], v209, s[24:25] offset:288
	s_mul_i32 s11, s20, 1
	s_add_i32 s11, s15, s11
	s_mul_i32 s11, s11, 0x12000
	s_add_u32 s40, s56, s11
	s_addc_u32 s41, s57, 0
	global_load_dwordx4 v[196:199], v140, s[40:41]
	global_load_dwordx4 v[200:203], v140, s[40:41] offset:64
	global_load_dwordx4 v[204:207], v140, s[40:41] offset:512
	global_load_dwordx4 v[212:215], v140, s[40:41] offset:576
	v_mov_b32_e32 v143, v141
	v_add_u32_e32 v132, 0x10000, v141
	v_add_u32_e32 v208, 0x20000, v141
	v_add_u32_e32 v209, 0x30000, v141
	s_waitcnt vmcnt(11)
	v_lshlrev_b32_e32 v148, 16, v150
	v_and_b32_e32 v149, 0xffff0000, v150
	v_lshlrev_b32_e32 v150, 16, v151
	v_and_b32_e32 v151, 0xffff0000, v151
	v_pk_fma_f32 v[148:149], v[180:181], v[124:125], v[148:149]
	v_pk_fma_f32 v[150:151], v[182:183], v[126:127], v[150:151]
	v_cvt_pk_bf16_f32 v148, v148, v149
	v_cvt_pk_bf16_f32 v149, v150, v151
	global_store_dwordx2 v143, v[148:149], s[24:25]
	global_load_dwordx2 v[150:151], v208, s[24:25]
	s_waitcnt vmcnt(12)
	v_lshlrev_b32_e32 v152, 16, v154
	v_and_b32_e32 v153, 0xffff0000, v154
	v_lshlrev_b32_e32 v154, 16, v155
	v_and_b32_e32 v155, 0xffff0000, v155
	v_pk_fma_f32 v[152:153], v[184:185], v[120:121], v[152:153]
	v_pk_fma_f32 v[154:155], v[186:187], v[122:123], v[154:155]
	v_cvt_pk_bf16_f32 v152, v152, v153
	v_cvt_pk_bf16_f32 v153, v154, v155
	global_store_dwordx2 v143, v[152:153], s[24:25] offset:32
	global_load_dwordx2 v[154:155], v208, s[24:25] offset:32
	s_waitcnt vmcnt(13)
	v_lshlrev_b32_e32 v156, 16, v158
	v_and_b32_e32 v157, 0xffff0000, v158
	v_lshlrev_b32_e32 v158, 16, v159
	v_and_b32_e32 v159, 0xffff0000, v159
	v_pk_fma_f32 v[156:157], v[188:189], v[112:113], v[156:157]
	v_pk_fma_f32 v[158:159], v[190:191], v[114:115], v[158:159]
	v_cvt_pk_bf16_f32 v156, v156, v157
	v_cvt_pk_bf16_f32 v157, v158, v159
	global_store_dwordx2 v143, v[156:157], s[24:25] offset:256
	global_load_dwordx2 v[158:159], v208, s[24:25] offset:256
	s_waitcnt vmcnt(14)
	v_lshlrev_b32_e32 v160, 16, v162
	v_and_b32_e32 v161, 0xffff0000, v162
	v_lshlrev_b32_e32 v162, 16, v163
	v_and_b32_e32 v163, 0xffff0000, v163
	v_pk_fma_f32 v[160:161], v[192:193], v[104:105], v[160:161]
	v_pk_fma_f32 v[162:163], v[194:195], v[106:107], v[162:163]
	v_cvt_pk_bf16_f32 v160, v160, v161
	v_cvt_pk_bf16_f32 v161, v162, v163
	global_store_dwordx2 v143, v[160:161], s[24:25] offset:288
	global_load_dwordx2 v[162:163], v208, s[24:25] offset:288
	s_waitcnt vmcnt(15)
	v_lshlrev_b32_e32 v164, 16, v166
	v_and_b32_e32 v165, 0xffff0000, v166
	v_lshlrev_b32_e32 v166, 16, v167
	v_and_b32_e32 v167, 0xffff0000, v167
	v_pk_fma_f32 v[164:165], v[180:181], v[116:117], v[164:165]
	v_pk_fma_f32 v[166:167], v[182:183], v[118:119], v[166:167]
	v_cvt_pk_bf16_f32 v164, v164, v165
	v_cvt_pk_bf16_f32 v165, v166, v167
	global_store_dwordx2 v132, v[164:165], s[24:25]
	global_load_dwordx2 v[166:167], v209, s[24:25]
	s_waitcnt vmcnt(16)
	v_lshlrev_b32_e32 v168, 16, v170
	v_and_b32_e32 v169, 0xffff0000, v170
	v_lshlrev_b32_e32 v170, 16, v171
	v_and_b32_e32 v171, 0xffff0000, v171
	v_pk_fma_f32 v[168:169], v[184:185], v[108:109], v[168:169]
	v_pk_fma_f32 v[170:171], v[186:187], v[110:111], v[170:171]
	v_cvt_pk_bf16_f32 v168, v168, v169
	v_cvt_pk_bf16_f32 v169, v170, v171
	global_store_dwordx2 v132, v[168:169], s[24:25] offset:32
	global_load_dwordx2 v[170:171], v209, s[24:25] offset:32
	s_waitcnt vmcnt(17)
	v_lshlrev_b32_e32 v172, 16, v174
	v_and_b32_e32 v173, 0xffff0000, v174
	v_lshlrev_b32_e32 v174, 16, v175
	v_and_b32_e32 v175, 0xffff0000, v175
	v_pk_fma_f32 v[172:173], v[188:189], v[100:101], v[172:173]
	v_pk_fma_f32 v[174:175], v[190:191], v[102:103], v[174:175]
	v_cvt_pk_bf16_f32 v172, v172, v173
	v_cvt_pk_bf16_f32 v173, v174, v175
	global_store_dwordx2 v132, v[172:173], s[24:25] offset:256
	global_load_dwordx2 v[174:175], v209, s[24:25] offset:256
	s_waitcnt vmcnt(18)
; __device__ __forceinline__ int fresh_tid() { int t = threadIdx.x; asm volatile("" : "+v"(t)); return t; }
; __device__ __forceinline__ unsigned cvt_pk_bf16(float lo, float hi) { unsigned r; asm volatile("v_cvt_pk_bf16_f32 %0, %1, %2" : "=v"(r) : "v"(lo), "v"(hi)); return r; }
;     __device__ __forceinline__ void operator()(const f32x4 (&acc)[2][2][4][2], const Unit& u, int wr, int wc, int fr_, int fq_) const {
;         (void)fr_; (void)fq_; const int l_ = fresh_tid() & 63, fr = l_ & 15, fq = l_ >> 4;
;         const int col0 = u.pn * BM + wc * 32 + 4 * fq;
;         const bool prm = u.pm < MP / BM;
; #pragma unroll
;         for (int ai = 0; ai < 2; ++ai)
; #pragma unroll
;             for (int m = 0; m < 4; ++m) {
;                 const int rl = ai * HALF + wr * 64 + m * 16 + fr, row = u.pm * BM + rl;
;                 const int b = prm ? (u.pm >> 3) : NB_P + (rl >> 5);
;                 const size_t xoff = (prm ? (size_t)row * D : (size_t)(row - MP) * D) + col0;
;                 const float* gr = gate + (size_t)b * NMOD + col0;
;                 bf16_t* orow = out + (size_t)row * D + col0;
; #pragma unroll
;                 for (int bj = 0; bj < 2; ++bj)
; #pragma unroll
;                     for (int n = 0; n < 2; ++n) { f32x4 xv;
;                         if (IN_F32) xv = *(const f32x4*)((const float*)(prm ? xin_p : xin_s) + xoff + bj * HALF + n * 16);
;                         else { const u32x2 w = *(const u32x2*)((const bf16_t*)(prm ? xin_p : xin_s) + xoff + bj * HALF + n * 16); xv = (f32x4){bflo(w.x), bfhi(w.x), bflo(w.y), bfhi(w.y)}; }
;                         const f32x4 gv = *(const f32x4*)(gr + bj * HALF + n * 16);
;                         const f32x4 r = xv + (gv * coef) * acc[ai][bj][m][n];
;                         u32x2 o; o.x = cvt_pk_bf16(r[0], r[1]); o.y = cvt_pk_bf16(r[2], r[3]); *(u32x2*)(orow + bj * HALF + n * 16) = o; }
;                 asm volatile("" ::: "memory"); }
;     }
	v_lshlrev_b32_e32 v176, 16, v178
	v_and_b32_e32 v177, 0xffff0000, v178
	v_lshlrev_b32_e32 v178, 16, v179
	v_and_b32_e32 v179, 0xffff0000, v179
	v_pk_fma_f32 v[176:177], v[192:193], v[88:89], v[176:177]
	v_pk_fma_f32 v[178:179], v[194:195], v[90:91], v[178:179]
	v_cvt_pk_bf16_f32 v176, v176, v177
	v_cvt_pk_bf16_f32 v177, v178, v179
	global_store_dwordx2 v132, v[176:177], s[24:25] offset:288
	global_load_dwordx2 v[178:179], v209, s[24:25] offset:288
	s_mul_i32 s11, s20, 4
	s_add_i32 s11, s15, s11
	s_mul_i32 s11, s11, 0x12000
	s_add_u32 s38, s56, s11
	s_addc_u32 s39, s57, 0
	global_load_dwordx4 v[180:183], v140, s[38:39]
	global_load_dwordx4 v[184:187], v140, s[38:39] offset:64
	global_load_dwordx4 v[188:191], v140, s[38:39] offset:512
	global_load_dwordx4 v[192:195], v140, s[38:39] offset:576
	v_add_u32_e32 v143, 0x20000, v141
	v_add_u32_e32 v132, 0x30000, v141
	v_add_u32_e32 v208, 0x80000, v141
	v_add_u32_e32 v209, 0x90000, v141
	s_waitcnt vmcnt(18)
	v_lshlrev_b32_e32 v148, 16, v150
	v_and_b32_e32 v149, 0xffff0000, v150
	v_lshlrev_b32_e32 v150, 16, v151
	v_and_b32_e32 v151, 0xffff0000, v151
	v_pk_fma_f32 v[148:149], v[196:197], v[96:97], v[148:149]
	v_pk_fma_f32 v[150:151], v[198:199], v[98:99], v[150:151]
	v_cvt_pk_bf16_f32 v148, v148, v149
	v_cvt_pk_bf16_f32 v149, v150, v151
	global_store_dwordx2 v143, v[148:149], s[24:25]
	global_load_dwordx2 v[150:151], v208, s[24:25]
	s_waitcnt vmcnt(18)
	v_lshlrev_b32_e32 v152, 16, v154
	v_and_b32_e32 v153, 0xffff0000, v154
	v_lshlrev_b32_e32 v154, 16, v155
	v_and_b32_e32 v155, 0xffff0000, v155
	v_pk_fma_f32 v[152:153], v[200:201], v[92:93], v[152:153]
	v_pk_fma_f32 v[154:155], v[202:203], v[94:95], v[154:155]
	v_cvt_pk_bf16_f32 v152, v152, v153
	v_cvt_pk_bf16_f32 v153, v154, v155
	global_store_dwordx2 v143, v[152:153], s[24:25] offset:32
	global_load_dwordx2 v[154:155], v208, s[24:25] offset:32
	s_waitcnt vmcnt(18)
	v_lshlrev_b32_e32 v156, 16, v158
	v_and_b32_e32 v157, 0xffff0000, v158
	v_lshlrev_b32_e32 v158, 16, v159
	v_and_b32_e32 v159, 0xffff0000, v159
	v_pk_fma_f32 v[156:157], v[204:205], v[84:85], v[156:157]
	v_pk_fma_f32 v[158:159], v[206:207], v[86:87], v[158:159]
	v_cvt_pk_bf16_f32 v156, v156, v157
	v_cvt_pk_bf16_f32 v157, v158, v159
	global_store_dwordx2 v143, v[156:157], s[24:25] offset:256
	global_load_dwordx2 v[158:159], v208, s[24:25] offset:256
	s_waitcnt vmcnt(18)
	v_lshlrev_b32_e32 v160, 16, v162
	v_and_b32_e32 v161, 0xffff0000, v162
	v_lshlrev_b32_e32 v162, 16, v163
	v_and_b32_e32 v163, 0xffff0000, v163
	v_pk_fma_f32 v[160:161], v[212:213], v[72:73], v[160:161]
	v_pk_fma_f32 v[162:163], v[214:215], v[74:75], v[162:163]
	v_cvt_pk_bf16_f32 v160, v160, v161
	v_cvt_pk_bf16_f32 v161, v162, v163
	global_store_dwordx2 v143, v[160:161], s[24:25] offset:288
	global_load_dwordx2 v[162:163], v208, s[24:25] offset:288
	s_waitcnt vmcnt(18)
	v_lshlrev_b32_e32 v164, 16, v166
	v_and_b32_e32 v165, 0xffff0000, v166
	v_lshlrev_b32_e32 v166, 16, v167
	v_and_b32_e32 v167, 0xffff0000, v167
	v_pk_fma_f32 v[164:165], v[196:197], v[80:81], v[164:165]
	v_pk_fma_f32 v[166:167], v[198:199], v[82:83], v[166:167]
	v_cvt_pk_bf16_f32 v164, v164, v165
	v_cvt_pk_bf16_f32 v165, v166, v167
	global_store_dwordx2 v132, v[164:165], s[24:25]
	global_load_dwordx2 v[166:167], v209, s[24:25]
	s_waitcnt vmcnt(18)
	v_lshlrev_b32_e32 v168, 16, v170
	v_and_b32_e32 v169, 0xffff0000, v170
	v_lshlrev_b32_e32 v170, 16, v171
	v_and_b32_e32 v171, 0xffff0000, v171
	v_pk_fma_f32 v[168:169], v[200:201], v[76:77], v[168:169]
	v_pk_fma_f32 v[170:171], v[202:203], v[78:79], v[170:171]
	v_cvt_pk_bf16_f32 v168, v168, v169
	v_cvt_pk_bf16_f32 v169, v170, v171
	global_store_dwordx2 v132, v[168:169], s[24:25] offset:32
	global_load_dwordx2 v[170:171], v209, s[24:25] offset:32
	s_waitcnt vmcnt(18)
	v_lshlrev_b32_e32 v172, 16, v174
	v_and_b32_e32 v173, 0xffff0000, v174
	v_lshlrev_b32_e32 v174, 16, v175
	v_and_b32_e32 v175, 0xffff0000, v175
	v_pk_fma_f32 v[172:173], v[204:205], v[68:69], v[172:173]
	v_pk_fma_f32 v[174:175], v[206:207], v[70:71], v[174:175]
	v_cvt_pk_bf16_f32 v172, v172, v173
	v_cvt_pk_bf16_f32 v173, v174, v175
	global_store_dwordx2 v132, v[172:173], s[24:25] offset:256
	global_load_dwordx2 v[174:175], v209, s[24:25] offset:256
	s_waitcnt vmcnt(18)
	v_lshlrev_b32_e32 v176, 16, v178
	v_and_b32_e32 v177, 0xffff0000, v178
	v_lshlrev_b32_e32 v178, 16, v179
	v_and_b32_e32 v179, 0xffff0000, v179
	v_pk_fma_f32 v[176:177], v[212:213], v[64:65], v[176:177]
	v_pk_fma_f32 v[178:179], v[214:215], v[66:67], v[178:179]
	v_cvt_pk_bf16_f32 v176, v176, v177
	v_cvt_pk_bf16_f32 v177, v178, v179
	global_store_dwordx2 v132, v[176:177], s[24:25] offset:288
	global_load_dwordx2 v[178:179], v209, s[24:25] offset:288
	s_mul_i32 s11, s20, 5
	s_add_i32 s11, s15, s11
	s_mul_i32 s11, s11, 0x12000
	s_add_u32 s40, s56, s11
	s_addc_u32 s41, s57, 0
	global_load_dwordx4 v[196:199], v140, s[40:41]
	global_load_dwordx4 v[200:203], v140, s[40:41] offset:64
	global_load_dwordx4 v[204:207], v140, s[40:41] offset:512
	global_load_dwordx4 v[212:215], v140, s[40:41] offset:576
	v_add_u32_e32 v143, 0x80000, v141
	v_add_u32_e32 v132, 0x90000, v141
	v_add_u32_e32 v208, 0xa0000, v141
	v_add_u32_e32 v209, 0xb0000, v141
	s_waitcnt vmcnt(18)
	v_lshlrev_b32_e32 v148, 16, v150
	v_and_b32_e32 v149, 0xffff0000, v150
	v_lshlrev_b32_e32 v150, 16, v151
	v_and_b32_e32 v151, 0xffff0000, v151
	v_pk_fma_f32 v[148:149], v[180:181], v[60:61], v[148:149]
	v_pk_fma_f32 v[150:151], v[182:183], v[62:63], v[150:151]
	v_cvt_pk_bf16_f32 v148, v148, v149
	v_cvt_pk_bf16_f32 v149, v150, v151
	global_store_dwordx2 v143, v[148:149], s[24:25]
	global_load_dwordx2 v[150:151], v208, s[24:25]
	s_waitcnt vmcnt(18)
; __device__ __forceinline__ int fresh_tid() { int t = threadIdx.x; asm volatile("" : "+v"(t)); return t; }
; __device__ __forceinline__ unsigned cvt_pk_bf16(float lo, float hi) { unsigned r; asm volatile("v_cvt_pk_bf16_f32 %0, %1, %2" : "=v"(r) : "v"(lo), "v"(hi)); return r; }
;     __device__ __forceinline__ void operator()(const f32x4 (&acc)[2][2][4][2], const Unit& u, int wr, int wc, int fr_, int fq_) const {
;         (void)fr_; (void)fq_; const int l_ = fresh_tid() & 63, fr = l_ & 15, fq = l_ >> 4;
;         const int col0 = u.pn * BM + wc * 32 + 4 * fq;
;         const bool prm = u.pm < MP / BM;
; #pragma unroll
;         for (int ai = 0; ai < 2; ++ai)
; #pragma unroll
;             for (int m = 0; m < 4; ++m) {
;                 const int rl = ai * HALF + wr * 64 + m * 16 + fr, row = u.pm * BM + rl;
;                 const int b = prm ? (u.pm >> 3) : NB_P + (rl >> 5);
;                 const size_t xoff = (prm ? (size_t)row * D : (size_t)(row - MP) * D) + col0;
;                 const float* gr = gate + (size_t)b * NMOD + col0;
;                 bf16_t* orow = out + (size_t)row * D + col0;
; #pragma unroll
;                 for (int bj = 0; bj < 2; ++bj)
; #pragma unroll
;                     for (int n = 0; n < 2; ++n) { f32x4 xv;
;                         if (IN_F32) xv = *(const f32x4*)((const float*)(prm ? xin_p : xin_s) + xoff + bj * HALF + n * 16);
;                         else { const u32x2 w = *(const u32x2*)((const bf16_t*)(prm ? xin_p : xin_s) + xoff + bj * HALF + n * 16); xv = (f32x4){bflo(w.x), bfhi(w.x), bflo(w.y), bfhi(w.y)}; }
;                         const f32x4 gv = *(const f32x4*)(gr + bj * HALF + n * 16);
;                         const f32x4 r = xv + (gv * coef) * acc[ai][bj][m][n];
;                         u32x2 o; o.x = cvt_pk_bf16(r[0], r[1]); o.y = cvt_pk_bf16(r[2], r[3]); *(u32x2*)(orow + bj * HALF + n * 16) = o; }
;                 asm volatile("" ::: "memory"); }
;     }
	v_lshlrev_b32_e32 v152, 16, v154
	v_and_b32_e32 v153, 0xffff0000, v154
	v_lshlrev_b32_e32 v154, 16, v155
	v_and_b32_e32 v155, 0xffff0000, v155
	v_pk_fma_f32 v[152:153], v[184:185], v[56:57], v[152:153]
	v_pk_fma_f32 v[154:155], v[186:187], v[58:59], v[154:155]
	v_cvt_pk_bf16_f32 v152, v152, v153
	v_cvt_pk_bf16_f32 v153, v154, v155
	global_store_dwordx2 v143, v[152:153], s[24:25] offset:32
	global_load_dwordx2 v[154:155], v208, s[24:25] offset:32
	s_waitcnt vmcnt(18)
	v_lshlrev_b32_e32 v156, 16, v158
	v_and_b32_e32 v157, 0xffff0000, v158
	v_lshlrev_b32_e32 v158, 16, v159
	v_and_b32_e32 v159, 0xffff0000, v159
	v_pk_fma_f32 v[156:157], v[188:189], v[52:53], v[156:157]
	v_pk_fma_f32 v[158:159], v[190:191], v[54:55], v[158:159]
	v_cvt_pk_bf16_f32 v156, v156, v157
	v_cvt_pk_bf16_f32 v157, v158, v159
	global_store_dwordx2 v143, v[156:157], s[24:25] offset:256
	global_load_dwordx2 v[158:159], v208, s[24:25] offset:256
	s_waitcnt vmcnt(18)
	v_lshlrev_b32_e32 v160, 16, v162
	v_and_b32_e32 v161, 0xffff0000, v162
	v_lshlrev_b32_e32 v162, 16, v163
	v_and_b32_e32 v163, 0xffff0000, v163
	v_pk_fma_f32 v[160:161], v[192:193], v[40:41], v[160:161]
	v_pk_fma_f32 v[162:163], v[194:195], v[42:43], v[162:163]
	v_cvt_pk_bf16_f32 v160, v160, v161
	v_cvt_pk_bf16_f32 v161, v162, v163
	global_store_dwordx2 v143, v[160:161], s[24:25] offset:288
	global_load_dwordx2 v[162:163], v208, s[24:25] offset:288
	s_waitcnt vmcnt(18)
	v_lshlrev_b32_e32 v164, 16, v166
	v_and_b32_e32 v165, 0xffff0000, v166
	v_lshlrev_b32_e32 v166, 16, v167
	v_and_b32_e32 v167, 0xffff0000, v167
	v_pk_fma_f32 v[164:165], v[180:181], v[48:49], v[164:165]
	v_pk_fma_f32 v[166:167], v[182:183], v[50:51], v[166:167]
	v_cvt_pk_bf16_f32 v164, v164, v165
	v_cvt_pk_bf16_f32 v165, v166, v167
	global_store_dwordx2 v132, v[164:165], s[24:25]
	global_load_dwordx2 v[166:167], v209, s[24:25]
	s_waitcnt vmcnt(18)
	v_lshlrev_b32_e32 v168, 16, v170
	v_and_b32_e32 v169, 0xffff0000, v170
	v_lshlrev_b32_e32 v170, 16, v171
	v_and_b32_e32 v171, 0xffff0000, v171
	v_pk_fma_f32 v[168:169], v[184:185], v[44:45], v[168:169]
	v_pk_fma_f32 v[170:171], v[186:187], v[46:47], v[170:171]
	v_cvt_pk_bf16_f32 v168, v168, v169
	v_cvt_pk_bf16_f32 v169, v170, v171
	global_store_dwordx2 v132, v[168:169], s[24:25] offset:32
	global_load_dwordx2 v[170:171], v209, s[24:25] offset:32
	s_waitcnt vmcnt(18)
	v_lshlrev_b32_e32 v172, 16, v174
	v_and_b32_e32 v173, 0xffff0000, v174
	v_lshlrev_b32_e32 v174, 16, v175
	v_and_b32_e32 v175, 0xffff0000, v175
	v_pk_fma_f32 v[172:173], v[188:189], v[36:37], v[172:173]
	v_pk_fma_f32 v[174:175], v[190:191], v[38:39], v[174:175]
	v_cvt_pk_bf16_f32 v172, v172, v173
	v_cvt_pk_bf16_f32 v173, v174, v175
	global_store_dwordx2 v132, v[172:173], s[24:25] offset:256
	global_load_dwordx2 v[174:175], v209, s[24:25] offset:256
	s_waitcnt vmcnt(18)
	v_lshlrev_b32_e32 v176, 16, v178
	v_and_b32_e32 v177, 0xffff0000, v178
	v_lshlrev_b32_e32 v178, 16, v179
	v_and_b32_e32 v179, 0xffff0000, v179
	v_pk_fma_f32 v[176:177], v[192:193], v[24:25], v[176:177]
	v_pk_fma_f32 v[178:179], v[194:195], v[26:27], v[178:179]
	v_cvt_pk_bf16_f32 v176, v176, v177
	v_cvt_pk_bf16_f32 v177, v178, v179
	global_store_dwordx2 v132, v[176:177], s[24:25] offset:288
	global_load_dwordx2 v[178:179], v209, s[24:25] offset:288
	v_add_u32_e32 v143, 0xa0000, v141
	v_add_u32_e32 v132, 0xb0000, v141
	s_waitcnt vmcnt(14)
	v_lshlrev_b32_e32 v148, 16, v150
	v_and_b32_e32 v149, 0xffff0000, v150
	v_lshlrev_b32_e32 v150, 16, v151
	v_and_b32_e32 v151, 0xffff0000, v151
	v_pk_fma_f32 v[148:149], v[196:197], v[32:33], v[148:149]
	v_pk_fma_f32 v[150:151], v[198:199], v[34:35], v[150:151]
	v_cvt_pk_bf16_f32 v148, v148, v149
	v_cvt_pk_bf16_f32 v149, v150, v151
	global_store_dwordx2 v143, v[148:149], s[24:25]
	s_waitcnt vmcnt(13)
	v_lshlrev_b32_e32 v152, 16, v154
	v_and_b32_e32 v153, 0xffff0000, v154
	v_lshlrev_b32_e32 v154, 16, v155
	v_and_b32_e32 v155, 0xffff0000, v155
	v_pk_fma_f32 v[152:153], v[200:201], v[28:29], v[152:153]
	v_pk_fma_f32 v[154:155], v[202:203], v[30:31], v[154:155]
	v_cvt_pk_bf16_f32 v152, v152, v153
	v_cvt_pk_bf16_f32 v153, v154, v155
	global_store_dwordx2 v143, v[152:153], s[24:25] offset:32
	s_waitcnt vmcnt(12)
	v_lshlrev_b32_e32 v156, 16, v158
	v_and_b32_e32 v157, 0xffff0000, v158
	v_lshlrev_b32_e32 v158, 16, v159
	v_and_b32_e32 v159, 0xffff0000, v159
	v_pk_fma_f32 v[156:157], v[204:205], v[20:21], v[156:157]
	v_pk_fma_f32 v[158:159], v[206:207], v[22:23], v[158:159]
	v_cvt_pk_bf16_f32 v156, v156, v157
	v_cvt_pk_bf16_f32 v157, v158, v159
	global_store_dwordx2 v143, v[156:157], s[24:25] offset:256
	s_waitcnt vmcnt(11)
	v_lshlrev_b32_e32 v160, 16, v162
	v_and_b32_e32 v161, 0xffff0000, v162
	v_lshlrev_b32_e32 v162, 16, v163
	v_and_b32_e32 v163, 0xffff0000, v163
	v_pk_fma_f32 v[160:161], v[212:213], v[8:9], v[160:161]
	v_pk_fma_f32 v[162:163], v[214:215], v[10:11], v[162:163]
	v_cvt_pk_bf16_f32 v160, v160, v161
	v_cvt_pk_bf16_f32 v161, v162, v163
	global_store_dwordx2 v143, v[160:161], s[24:25] offset:288
	s_waitcnt vmcnt(10)
	v_lshlrev_b32_e32 v164, 16, v166
	v_and_b32_e32 v165, 0xffff0000, v166
	v_lshlrev_b32_e32 v166, 16, v167
	v_and_b32_e32 v167, 0xffff0000, v167
	v_pk_fma_f32 v[164:165], v[196:197], v[16:17], v[164:165]
	v_pk_fma_f32 v[166:167], v[198:199], v[18:19], v[166:167]
	v_cvt_pk_bf16_f32 v164, v164, v165
	v_cvt_pk_bf16_f32 v165, v166, v167
	global_store_dwordx2 v132, v[164:165], s[24:25]
	s_waitcnt vmcnt(9)
	v_lshlrev_b32_e32 v168, 16, v170
	v_and_b32_e32 v169, 0xffff0000, v170
	v_lshlrev_b32_e32 v170, 16, v171
	v_and_b32_e32 v171, 0xffff0000, v171
	v_pk_fma_f32 v[168:169], v[200:201], v[12:13], v[168:169]
	v_pk_fma_f32 v[170:171], v[202:203], v[14:15], v[170:171]
	v_cvt_pk_bf16_f32 v168, v168, v169
	v_cvt_pk_bf16_f32 v169, v170, v171
	global_store_dwordx2 v132, v[168:169], s[24:25] offset:32
	s_waitcnt vmcnt(8)
	v_lshlrev_b32_e32 v172, 16, v174
	v_and_b32_e32 v173, 0xffff0000, v174
	v_lshlrev_b32_e32 v174, 16, v175
	v_and_b32_e32 v175, 0xffff0000, v175
	v_pk_fma_f32 v[172:173], v[204:205], v[4:5], v[172:173]
	v_pk_fma_f32 v[174:175], v[206:207], v[6:7], v[174:175]
	v_cvt_pk_bf16_f32 v172, v172, v173
	v_cvt_pk_bf16_f32 v173, v174, v175
	global_store_dwordx2 v132, v[172:173], s[24:25] offset:256
	s_waitcnt vmcnt(7)
	v_lshlrev_b32_e32 v176, 16, v178
	v_and_b32_e32 v177, 0xffff0000, v178
	v_lshlrev_b32_e32 v178, 16, v179
	v_and_b32_e32 v179, 0xffff0000, v179
	v_pk_fma_f32 v[176:177], v[212:213], v[0:1], v[176:177]
	v_pk_fma_f32 v[178:179], v[214:215], v[2:3], v[178:179]
	v_cvt_pk_bf16_f32 v176, v176, v177
	v_cvt_pk_bf16_f32 v177, v178, v179
	global_store_dwordx2 v132, v[176:177], s[24:25] offset:288

; __device__ __forceinline__ int fresh_tid() { int t = threadIdx.x; asm volatile("" : "+v"(t)); return t; }
; __device__ __forceinline__ unsigned cvt_pk_bf16(float lo, float hi) { unsigned r; asm volatile("v_cvt_pk_bf16_f32 %0, %1, %2" : "=v"(r) : "v"(lo), "v"(hi)); return r; }
;     __device__ __forceinline__ void operator()(const f32x4 (&acc)[2][2][4][2], const Unit& u, int wr, int wc, int fr_, int fq_) const {
;         (void)fr_; (void)fq_; const int l_ = fresh_tid() & 63, fr = l_ & 15, fq = l_ >> 4;
;         const int col0 = u.pn * BM + wc * 32 + 4 * fq;
;         const bool prm = u.pm < MP / BM;
; #pragma unroll
;         for (int ai = 0; ai < 2; ++ai)
; #pragma unroll
;             for (int m = 0; m < 4; ++m) {
;                 const int rl = ai * HALF + wr * 64 + m * 16 + fr, row = u.pm * BM + rl;
;                 const int b = prm ? (u.pm >> 3) : NB_P + (rl >> 5);
;                 const size_t xoff = (prm ? (size_t)row * D : (size_t)(row - MP) * D) + col0;
;                 const float* gr = gate + (size_t)b * NMOD + col0;
;                 bf16_t* orow = out + (size_t)row * D + col0;
; #pragma unroll
;                 for (int bj = 0; bj < 2; ++bj)
; #pragma unroll
;                     for (int n = 0; n < 2; ++n) { f32x4 xv;
;                         if (IN_F32) xv = *(const f32x4*)((const float*)(prm ? xin_p : xin_s) + xoff + bj * HALF + n * 16);
;                         else { const u32x2 w = *(const u32x2*)((const bf16_t*)(prm ? xin_p : xin_s) + xoff + bj * HALF + n * 16); xv = (f32x4){bflo(w.x), bfhi(w.x), bflo(w.y), bfhi(w.y)}; }
;                         const f32x4 gv = *(const f32x4*)(gr + bj * HALF + n * 16);
;                         const f32x4 r = xv + (gv * coef) * acc[ai][bj][m][n];
;                         u32x2 o; o.x = cvt_pk_bf16(r[0], r[1]); o.y = cvt_pk_bf16(r[2], r[3]); *(u32x2*)(orow + bj * HALF + n * 16) = o; }
;                 asm volatile("" ::: "memory"); }
;     }
.LBB0_1343:
	s_and_b64 vcc, exec, s[22:23]
	s_cbranch_vccz .LBB0_1345
	v_and_b32_e32 v175, 15, v210
	v_lshrrev_b32_e32 v172, 2, v210
	v_and_b32_e32 v172, 12, v172
	v_or_b32_e32 v172, s52, v172
	s_lshl_b32 s15, s81, 8
	v_or_b32_e32 v172, s15, v172
	v_or_b32_e32 v175, s51, v175
	s_lshl_b32 s15, s82, 8
	v_add_u32_e32 v175, s15, v175
	v_lshlrev_b32_e32 v173, 12, v175
	v_lshl_add_u32 v173, v172, 1, v173
	s_lshr_b32 s20, s51, 5
	s_add_i32 s20, s20, 16
	s_ashr_i32 s15, s82, 3
	s_cmpk_lt_i32 s82, 0x80
	s_cselect_b32 s36, s15, s20
	s_cselect_b32 s37, 0, 1
	v_lshlrev_b32_e32 v172, 2, v172
	s_mul_i32 s15, s36, 0x12000
	s_add_u32 s22, s45, s15
	s_addc_u32 s23, s48, 0
	global_load_dwordx4 v[184:187], v172, s[22:23]
	global_load_dwordx4 v[188:191], v172, s[22:23] offset:64
	global_load_dwordx4 v[192:195], v172, s[22:23] offset:512
	global_load_dwordx4 v[196:199], v172, s[22:23] offset:576
	v_mov_b32_e32 v178, v173
	v_add_u32_e32 v179, 0x10000, v173
	global_load_dwordx2 v[2:3], v178, s[24:25]
	global_load_dwordx2 v[6:7], v178, s[24:25] offset:32
	global_load_dwordx2 v[10:11], v178, s[24:25] offset:256
	global_load_dwordx2 v[14:15], v178, s[24:25] offset:288
	global_load_dwordx2 v[18:19], v179, s[24:25]
	global_load_dwordx2 v[22:23], v179, s[24:25] offset:32
	global_load_dwordx2 v[26:27], v179, s[24:25] offset:256
	global_load_dwordx2 v[30:31], v179, s[24:25] offset:288
	s_mul_i32 s15, s37, 1
	s_add_i32 s15, s36, s15
	s_mul_i32 s15, s15, 0x12000
	s_add_u32 s34, s45, s15
	s_addc_u32 s35, s48, 0
	global_load_dwordx4 v[200:203], v172, s[34:35]
	global_load_dwordx4 v[204:207], v172, s[34:35] offset:64
	global_load_dwordx4 v[212:215], v172, s[34:35] offset:512
	global_load_dwordx4 v[216:219], v172, s[34:35] offset:576
	v_mov_b32_e32 v176, v173
	v_add_u32_e32 v177, 0x10000, v173
	v_add_u32_e32 v178, 0x20000, v173
	v_add_u32_e32 v179, 0x30000, v173
	s_waitcnt vmcnt(11)
	v_pk_mul_f32 v[184:185], v[184:185], s[12:13] op_sel_hi:[1,0]
	v_pk_mul_f32 v[186:187], v[186:187], s[12:13] op_sel_hi:[1,0]
	v_pk_mul_f32 v[188:189], v[188:189], s[12:13] op_sel_hi:[1,0]
	v_pk_mul_f32 v[190:191], v[190:191], s[12:13] op_sel_hi:[1,0]
	v_pk_mul_f32 v[192:193], v[192:193], s[12:13] op_sel_hi:[1,0]
	v_pk_mul_f32 v[194:195], v[194:195], s[12:13] op_sel_hi:[1,0]
	v_pk_mul_f32 v[196:197], v[196:197], s[12:13] op_sel_hi:[1,0]
	v_pk_mul_f32 v[198:199], v[198:199], s[12:13] op_sel_hi:[1,0]
	v_lshlrev_b32_e32 v0, 16, v2
	v_and_b32_e32 v1, 0xffff0000, v2
	v_lshlrev_b32_e32 v2, 16, v3
	v_and_b32_e32 v3, 0xffff0000, v3
	v_pk_fma_f32 v[0:1], v[184:185], v[156:157], v[0:1]
	v_pk_fma_f32 v[2:3], v[186:187], v[158:159], v[2:3]
	v_cvt_pk_bf16_f32 v0, v0, v1
	v_cvt_pk_bf16_f32 v1, v2, v3
	global_store_dwordx2 v176, v[0:1], s[24:25]
	global_load_dwordx2 v[2:3], v178, s[24:25]
	s_waitcnt vmcnt(12)
	v_lshlrev_b32_e32 v4, 16, v6
	v_and_b32_e32 v5, 0xffff0000, v6
	v_lshlrev_b32_e32 v6, 16, v7
	v_and_b32_e32 v7, 0xffff0000, v7
	v_pk_fma_f32 v[4:5], v[188:189], v[152:153], v[4:5]
	v_pk_fma_f32 v[6:7], v[190:191], v[154:155], v[6:7]
	v_cvt_pk_bf16_f32 v4, v4, v5
	v_cvt_pk_bf16_f32 v5, v6, v7
	global_store_dwordx2 v176, v[4:5], s[24:25] offset:32
	global_load_dwordx2 v[6:7], v178, s[24:25] offset:32
	s_waitcnt vmcnt(13)
	v_lshlrev_b32_e32 v8, 16, v10
	v_and_b32_e32 v9, 0xffff0000, v10
	v_lshlrev_b32_e32 v10, 16, v11
	v_and_b32_e32 v11, 0xffff0000, v11
	v_pk_fma_f32 v[8:9], v[192:193], v[148:149], v[8:9]
	v_pk_fma_f32 v[10:11], v[194:195], v[150:151], v[10:11]
	v_cvt_pk_bf16_f32 v8, v8, v9
	v_cvt_pk_bf16_f32 v9, v10, v11
	global_store_dwordx2 v176, v[8:9], s[24:25] offset:256
	global_load_dwordx2 v[10:11], v178, s[24:25] offset:256
	s_waitcnt vmcnt(14)
	v_lshlrev_b32_e32 v12, 16, v14
	v_and_b32_e32 v13, 0xffff0000, v14
	v_lshlrev_b32_e32 v14, 16, v15
	v_and_b32_e32 v15, 0xffff0000, v15
	v_pk_fma_f32 v[12:13], v[196:197], v[136:137], v[12:13]
	v_pk_fma_f32 v[14:15], v[198:199], v[138:139], v[14:15]
	v_cvt_pk_bf16_f32 v12, v12, v13
	v_cvt_pk_bf16_f32 v13, v14, v15
	global_store_dwordx2 v176, v[12:13], s[24:25] offset:288
	global_load_dwordx2 v[14:15], v178, s[24:25] offset:288
	s_waitcnt vmcnt(15)
	v_lshlrev_b32_e32 v16, 16, v18
	v_and_b32_e32 v17, 0xffff0000, v18
	v_lshlrev_b32_e32 v18, 16, v19
	v_and_b32_e32 v19, 0xffff0000, v19
	v_pk_fma_f32 v[16:17], v[184:185], v[144:145], v[16:17]
	v_pk_fma_f32 v[18:19], v[186:187], v[146:147], v[18:19]
	v_cvt_pk_bf16_f32 v16, v16, v17
	v_cvt_pk_bf16_f32 v17, v18, v19
	global_store_dwordx2 v177, v[16:17], s[24:25]
	global_load_dwordx2 v[18:19], v179, s[24:25]
	s_waitcnt vmcnt(16)
	v_lshlrev_b32_e32 v20, 16, v22
	v_and_b32_e32 v21, 0xffff0000, v22
	v_lshlrev_b32_e32 v22, 16, v23
	v_and_b32_e32 v23, 0xffff0000, v23
	v_pk_fma_f32 v[20:21], v[188:189], v[140:141], v[20:21]
	v_pk_fma_f32 v[22:23], v[190:191], v[142:143], v[22:23]
	v_cvt_pk_bf16_f32 v20, v20, v21
	v_cvt_pk_bf16_f32 v21, v22, v23
	global_store_dwordx2 v177, v[20:21], s[24:25] offset:32
	global_load_dwordx2 v[22:23], v179, s[24:25] offset:32
	s_waitcnt vmcnt(17)
	v_lshlrev_b32_e32 v24, 16, v26
	v_and_b32_e32 v25, 0xffff0000, v26
	v_lshlrev_b32_e32 v26, 16, v27
	v_and_b32_e32 v27, 0xffff0000, v27
	v_pk_fma_f32 v[24:25], v[192:193], v[132:133], v[24:25]
	v_pk_fma_f32 v[26:27], v[194:195], v[134:135], v[26:27]
	v_cvt_pk_bf16_f32 v24, v24, v25
	v_cvt_pk_bf16_f32 v25, v26, v27
	global_store_dwordx2 v177, v[24:25], s[24:25] offset:256
	global_load_dwordx2 v[26:27], v179, s[24:25] offset:256
	s_waitcnt vmcnt(18)
; __device__ __forceinline__ int fresh_tid() { int t = threadIdx.x; asm volatile("" : "+v"(t)); return t; }
; __device__ __forceinline__ unsigned cvt_pk_bf16(float lo, float hi) { unsigned r; asm volatile("v_cvt_pk_bf16_f32 %0, %1, %2" : "=v"(r) : "v"(lo), "v"(hi)); return r; }
;     __device__ __forceinline__ void operator()(const f32x4 (&acc)[2][2][4][2], const Unit& u, int wr, int wc, int fr_, int fq_) const {
;         (void)fr_; (void)fq_; const int l_ = fresh_tid() & 63, fr = l_ & 15, fq = l_ >> 4;
;         const int col0 = u.pn * BM + wc * 32 + 4 * fq;
;         const bool prm = u.pm < MP / BM;
; #pragma unroll
;         for (int ai = 0; ai < 2; ++ai)
; #pragma unroll
;             for (int m = 0; m < 4; ++m) {
;                 const int rl = ai * HALF + wr * 64 + m * 16 + fr, row = u.pm * BM + rl;
;                 const int b = prm ? (u.pm >> 3) : NB_P + (rl >> 5);
;                 const size_t xoff = (prm ? (size_t)row * D : (size_t)(row - MP) * D) + col0;
;                 const float* gr = gate + (size_t)b * NMOD + col0;
;                 bf16_t* orow = out + (size_t)row * D + col0;
; #pragma unroll
;                 for (int bj = 0; bj < 2; ++bj)
; #pragma unroll
;                     for (int n = 0; n < 2; ++n) { f32x4 xv;
;                         if (IN_F32) xv = *(const f32x4*)((const float*)(prm ? xin_p : xin_s) + xoff + bj * HALF + n * 16);
;                         else { const u32x2 w = *(const u32x2*)((const bf16_t*)(prm ? xin_p : xin_s) + xoff + bj * HALF + n * 16); xv = (f32x4){bflo(w.x), bfhi(w.x), bflo(w.y), bfhi(w.y)}; }
;                         const f32x4 gv = *(const f32x4*)(gr + bj * HALF + n * 16);
;                         const f32x4 r = xv + (gv * coef) * acc[ai][bj][m][n];
;                         u32x2 o; o.x = cvt_pk_bf16(r[0], r[1]); o.y = cvt_pk_bf16(r[2], r[3]); *(u32x2*)(orow + bj * HALF + n * 16) = o; }
;                 asm volatile("" ::: "memory"); }
;     }
	v_lshlrev_b32_e32 v28, 16, v30
	v_and_b32_e32 v29, 0xffff0000, v30
	v_lshlrev_b32_e32 v30, 16, v31
	v_and_b32_e32 v31, 0xffff0000, v31
	v_pk_fma_f32 v[28:29], v[196:197], v[120:121], v[28:29]
	v_pk_fma_f32 v[30:31], v[198:199], v[122:123], v[30:31]
	v_cvt_pk_bf16_f32 v28, v28, v29
	v_cvt_pk_bf16_f32 v29, v30, v31
	global_store_dwordx2 v177, v[28:29], s[24:25] offset:288
	global_load_dwordx2 v[30:31], v179, s[24:25] offset:288
	s_mul_i32 s15, s37, 4
	s_add_i32 s15, s36, s15
	s_mul_i32 s15, s15, 0x12000
	s_add_u32 s22, s45, s15
	s_addc_u32 s23, s48, 0
	global_load_dwordx4 v[184:187], v172, s[22:23]
	global_load_dwordx4 v[188:191], v172, s[22:23] offset:64
	global_load_dwordx4 v[192:195], v172, s[22:23] offset:512
	global_load_dwordx4 v[196:199], v172, s[22:23] offset:576
	v_add_u32_e32 v176, 0x20000, v173
	v_add_u32_e32 v177, 0x30000, v173
	v_add_u32_e32 v178, 0x80000, v173
	v_add_u32_e32 v179, 0x90000, v173
	s_waitcnt vmcnt(18)
	v_pk_mul_f32 v[200:201], v[200:201], s[12:13] op_sel_hi:[1,0]
	v_pk_mul_f32 v[202:203], v[202:203], s[12:13] op_sel_hi:[1,0]
	v_pk_mul_f32 v[204:205], v[204:205], s[12:13] op_sel_hi:[1,0]
	v_pk_mul_f32 v[206:207], v[206:207], s[12:13] op_sel_hi:[1,0]
	v_pk_mul_f32 v[212:213], v[212:213], s[12:13] op_sel_hi:[1,0]
	v_pk_mul_f32 v[214:215], v[214:215], s[12:13] op_sel_hi:[1,0]
	v_pk_mul_f32 v[216:217], v[216:217], s[12:13] op_sel_hi:[1,0]
	v_pk_mul_f32 v[218:219], v[218:219], s[12:13] op_sel_hi:[1,0]
	v_lshlrev_b32_e32 v0, 16, v2
	v_and_b32_e32 v1, 0xffff0000, v2
	v_lshlrev_b32_e32 v2, 16, v3
	v_and_b32_e32 v3, 0xffff0000, v3
	v_pk_fma_f32 v[0:1], v[200:201], v[128:129], v[0:1]
	v_pk_fma_f32 v[2:3], v[202:203], v[130:131], v[2:3]
	v_cvt_pk_bf16_f32 v0, v0, v1
	v_cvt_pk_bf16_f32 v1, v2, v3
	global_store_dwordx2 v176, v[0:1], s[24:25]
	global_load_dwordx2 v[2:3], v178, s[24:25]
	s_waitcnt vmcnt(18)
	v_lshlrev_b32_e32 v4, 16, v6
	v_and_b32_e32 v5, 0xffff0000, v6
	v_lshlrev_b32_e32 v6, 16, v7
	v_and_b32_e32 v7, 0xffff0000, v7
	v_pk_fma_f32 v[4:5], v[204:205], v[124:125], v[4:5]
	v_pk_fma_f32 v[6:7], v[206:207], v[126:127], v[6:7]
	v_cvt_pk_bf16_f32 v4, v4, v5
	v_cvt_pk_bf16_f32 v5, v6, v7
	global_store_dwordx2 v176, v[4:5], s[24:25] offset:32
	global_load_dwordx2 v[6:7], v178, s[24:25] offset:32
	s_waitcnt vmcnt(18)
	v_lshlrev_b32_e32 v8, 16, v10
	v_and_b32_e32 v9, 0xffff0000, v10
	v_lshlrev_b32_e32 v10, 16, v11
	v_and_b32_e32 v11, 0xffff0000, v11
	v_pk_fma_f32 v[8:9], v[212:213], v[116:117], v[8:9]
	v_pk_fma_f32 v[10:11], v[214:215], v[118:119], v[10:11]
	v_cvt_pk_bf16_f32 v8, v8, v9
	v_cvt_pk_bf16_f32 v9, v10, v11
	global_store_dwordx2 v176, v[8:9], s[24:25] offset:256
	global_load_dwordx2 v[10:11], v178, s[24:25] offset:256
	s_waitcnt vmcnt(18)
	v_lshlrev_b32_e32 v12, 16, v14
	v_and_b32_e32 v13, 0xffff0000, v14
	v_lshlrev_b32_e32 v14, 16, v15
	v_and_b32_e32 v15, 0xffff0000, v15
	v_pk_fma_f32 v[12:13], v[216:217], v[104:105], v[12:13]
	v_pk_fma_f32 v[14:15], v[218:219], v[106:107], v[14:15]
	v_cvt_pk_bf16_f32 v12, v12, v13
	v_cvt_pk_bf16_f32 v13, v14, v15
	global_store_dwordx2 v176, v[12:13], s[24:25] offset:288
	global_load_dwordx2 v[14:15], v178, s[24:25] offset:288
	s_waitcnt vmcnt(18)
	v_lshlrev_b32_e32 v16, 16, v18
	v_and_b32_e32 v17, 0xffff0000, v18
	v_lshlrev_b32_e32 v18, 16, v19
	v_and_b32_e32 v19, 0xffff0000, v19
	v_pk_fma_f32 v[16:17], v[200:201], v[112:113], v[16:17]
	v_pk_fma_f32 v[18:19], v[202:203], v[114:115], v[18:19]
	v_cvt_pk_bf16_f32 v16, v16, v17
	v_cvt_pk_bf16_f32 v17, v18, v19
	global_store_dwordx2 v177, v[16:17], s[24:25]
	global_load_dwordx2 v[18:19], v179, s[24:25]
	s_waitcnt vmcnt(18)
	v_lshlrev_b32_e32 v20, 16, v22
	v_and_b32_e32 v21, 0xffff0000, v22
	v_lshlrev_b32_e32 v22, 16, v23
	v_and_b32_e32 v23, 0xffff0000, v23
	v_pk_fma_f32 v[20:21], v[204:205], v[108:109], v[20:21]
	v_pk_fma_f32 v[22:23], v[206:207], v[110:111], v[22:23]
	v_cvt_pk_bf16_f32 v20, v20, v21
	v_cvt_pk_bf16_f32 v21, v22, v23
	global_store_dwordx2 v177, v[20:21], s[24:25] offset:32
	global_load_dwordx2 v[22:23], v179, s[24:25] offset:32
	s_waitcnt vmcnt(18)
	v_lshlrev_b32_e32 v24, 16, v26
	v_and_b32_e32 v25, 0xffff0000, v26
	v_lshlrev_b32_e32 v26, 16, v27
	v_and_b32_e32 v27, 0xffff0000, v27
	v_pk_fma_f32 v[24:25], v[212:213], v[100:101], v[24:25]
	v_pk_fma_f32 v[26:27], v[214:215], v[102:103], v[26:27]
	v_cvt_pk_bf16_f32 v24, v24, v25
	v_cvt_pk_bf16_f32 v25, v26, v27
	global_store_dwordx2 v177, v[24:25], s[24:25] offset:256
	global_load_dwordx2 v[26:27], v179, s[24:25] offset:256
	s_waitcnt vmcnt(18)
	v_lshlrev_b32_e32 v28, 16, v30
	v_and_b32_e32 v29, 0xffff0000, v30
	v_lshlrev_b32_e32 v30, 16, v31
	v_and_b32_e32 v31, 0xffff0000, v31
	v_pk_fma_f32 v[28:29], v[216:217], v[96:97], v[28:29]
	v_pk_fma_f32 v[30:31], v[218:219], v[98:99], v[30:31]
	v_cvt_pk_bf16_f32 v28, v28, v29
	v_cvt_pk_bf16_f32 v29, v30, v31
	global_store_dwordx2 v177, v[28:29], s[24:25] offset:288
	global_load_dwordx2 v[30:31], v179, s[24:25] offset:288
	s_mul_i32 s15, s37, 5
	s_add_i32 s15, s36, s15
	s_mul_i32 s15, s15, 0x12000
	s_add_u32 s34, s45, s15
	s_addc_u32 s35, s48, 0
	global_load_dwordx4 v[200:203], v172, s[34:35]
	global_load_dwordx4 v[204:207], v172, s[34:35] offset:64
	global_load_dwordx4 v[212:215], v172, s[34:35] offset:512
	global_load_dwordx4 v[216:219], v172, s[34:35] offset:576
	v_add_u32_e32 v176, 0x80000, v173
	v_add_u32_e32 v177, 0x90000, v173
	v_add_u32_e32 v178, 0xa0000, v173
	v_add_u32_e32 v179, 0xb0000, v173
	s_waitcnt vmcnt(18)
; __device__ __forceinline__ int fresh_tid() { int t = threadIdx.x; asm volatile("" : "+v"(t)); return t; }
; __device__ __forceinline__ unsigned cvt_pk_bf16(float lo, float hi) { unsigned r; asm volatile("v_cvt_pk_bf16_f32 %0, %1, %2" : "=v"(r) : "v"(lo), "v"(hi)); return r; }
;     __device__ __forceinline__ void operator()(const f32x4 (&acc)[2][2][4][2], const Unit& u, int wr, int wc, int fr_, int fq_) const {
;         (void)fr_; (void)fq_; const int l_ = fresh_tid() & 63, fr = l_ & 15, fq = l_ >> 4;
;         const int col0 = u.pn * BM + wc * 32 + 4 * fq;
;         const bool prm = u.pm < MP / BM;
; #pragma unroll
;         for (int ai = 0; ai < 2; ++ai)
; #pragma unroll
;             for (int m = 0; m < 4; ++m) {
;                 const int rl = ai * HALF + wr * 64 + m * 16 + fr, row = u.pm * BM + rl;
;                 const int b = prm ? (u.pm >> 3) : NB_P + (rl >> 5);
;                 const size_t xoff = (prm ? (size_t)row * D : (size_t)(row - MP) * D) + col0;
;                 const float* gr = gate + (size_t)b * NMOD + col0;
;                 bf16_t* orow = out + (size_t)row * D + col0;
; #pragma unroll
;                 for (int bj = 0; bj < 2; ++bj)
; #pragma unroll
;                     for (int n = 0; n < 2; ++n) { f32x4 xv;
;                         if (IN_F32) xv = *(const f32x4*)((const float*)(prm ? xin_p : xin_s) + xoff + bj * HALF + n * 16);
;                         else { const u32x2 w = *(const u32x2*)((const bf16_t*)(prm ? xin_p : xin_s) + xoff + bj * HALF + n * 16); xv = (f32x4){bflo(w.x), bfhi(w.x), bflo(w.y), bfhi(w.y)}; }
;                         const f32x4 gv = *(const f32x4*)(gr + bj * HALF + n * 16);
;                         const f32x4 r = xv + (gv * coef) * acc[ai][bj][m][n];
;                         u32x2 o; o.x = cvt_pk_bf16(r[0], r[1]); o.y = cvt_pk_bf16(r[2], r[3]); *(u32x2*)(orow + bj * HALF + n * 16) = o; }
;                 asm volatile("" ::: "memory"); }
;     }
	v_pk_mul_f32 v[184:185], v[184:185], s[12:13] op_sel_hi:[1,0]
	v_pk_mul_f32 v[186:187], v[186:187], s[12:13] op_sel_hi:[1,0]
	v_pk_mul_f32 v[188:189], v[188:189], s[12:13] op_sel_hi:[1,0]
	v_pk_mul_f32 v[190:191], v[190:191], s[12:13] op_sel_hi:[1,0]
	v_pk_mul_f32 v[192:193], v[192:193], s[12:13] op_sel_hi:[1,0]
	v_pk_mul_f32 v[194:195], v[194:195], s[12:13] op_sel_hi:[1,0]
	v_pk_mul_f32 v[196:197], v[196:197], s[12:13] op_sel_hi:[1,0]
	v_pk_mul_f32 v[198:199], v[198:199], s[12:13] op_sel_hi:[1,0]
	v_lshlrev_b32_e32 v0, 16, v2
	v_and_b32_e32 v1, 0xffff0000, v2
	v_lshlrev_b32_e32 v2, 16, v3
	v_and_b32_e32 v3, 0xffff0000, v3
	v_pk_fma_f32 v[0:1], v[184:185], v[92:93], v[0:1]
	v_pk_fma_f32 v[2:3], v[186:187], v[94:95], v[2:3]
	v_cvt_pk_bf16_f32 v0, v0, v1
	v_cvt_pk_bf16_f32 v1, v2, v3
	global_store_dwordx2 v176, v[0:1], s[24:25]
	global_load_dwordx2 v[2:3], v178, s[24:25]
	s_waitcnt vmcnt(18)
	v_lshlrev_b32_e32 v4, 16, v6
	v_and_b32_e32 v5, 0xffff0000, v6
	v_lshlrev_b32_e32 v6, 16, v7
	v_and_b32_e32 v7, 0xffff0000, v7
	v_pk_fma_f32 v[4:5], v[188:189], v[88:89], v[4:5]
	v_pk_fma_f32 v[6:7], v[190:191], v[90:91], v[6:7]
	v_cvt_pk_bf16_f32 v4, v4, v5
	v_cvt_pk_bf16_f32 v5, v6, v7
	global_store_dwordx2 v176, v[4:5], s[24:25] offset:32
	global_load_dwordx2 v[6:7], v178, s[24:25] offset:32
	s_waitcnt vmcnt(18)
	v_lshlrev_b32_e32 v8, 16, v10
	v_and_b32_e32 v9, 0xffff0000, v10
	v_lshlrev_b32_e32 v10, 16, v11
	v_and_b32_e32 v11, 0xffff0000, v11
	v_pk_fma_f32 v[8:9], v[192:193], v[84:85], v[8:9]
	v_pk_fma_f32 v[10:11], v[194:195], v[86:87], v[10:11]
	v_cvt_pk_bf16_f32 v8, v8, v9
	v_cvt_pk_bf16_f32 v9, v10, v11
	global_store_dwordx2 v176, v[8:9], s[24:25] offset:256
	global_load_dwordx2 v[10:11], v178, s[24:25] offset:256
	s_waitcnt vmcnt(18)
	v_lshlrev_b32_e32 v12, 16, v14
	v_and_b32_e32 v13, 0xffff0000, v14
	v_lshlrev_b32_e32 v14, 16, v15
	v_and_b32_e32 v15, 0xffff0000, v15
	v_pk_fma_f32 v[12:13], v[196:197], v[72:73], v[12:13]
	v_pk_fma_f32 v[14:15], v[198:199], v[74:75], v[14:15]
	v_cvt_pk_bf16_f32 v12, v12, v13
	v_cvt_pk_bf16_f32 v13, v14, v15
	global_store_dwordx2 v176, v[12:13], s[24:25] offset:288
	global_load_dwordx2 v[14:15], v178, s[24:25] offset:288
	s_waitcnt vmcnt(18)
	v_lshlrev_b32_e32 v16, 16, v18
	v_and_b32_e32 v17, 0xffff0000, v18
	v_lshlrev_b32_e32 v18, 16, v19
	v_and_b32_e32 v19, 0xffff0000, v19
	v_pk_fma_f32 v[16:17], v[184:185], v[80:81], v[16:17]
	v_pk_fma_f32 v[18:19], v[186:187], v[82:83], v[18:19]
	v_cvt_pk_bf16_f32 v16, v16, v17
	v_cvt_pk_bf16_f32 v17, v18, v19
	global_store_dwordx2 v177, v[16:17], s[24:25]
	global_load_dwordx2 v[18:19], v179, s[24:25]
	s_waitcnt vmcnt(18)
	v_lshlrev_b32_e32 v20, 16, v22
	v_and_b32_e32 v21, 0xffff0000, v22
	v_lshlrev_b32_e32 v22, 16, v23
	v_and_b32_e32 v23, 0xffff0000, v23
	v_pk_fma_f32 v[20:21], v[188:189], v[76:77], v[20:21]
	v_pk_fma_f32 v[22:23], v[190:191], v[78:79], v[22:23]
	v_cvt_pk_bf16_f32 v20, v20, v21
	v_cvt_pk_bf16_f32 v21, v22, v23
	global_store_dwordx2 v177, v[20:21], s[24:25] offset:32
	global_load_dwordx2 v[22:23], v179, s[24:25] offset:32
	s_waitcnt vmcnt(18)
	v_lshlrev_b32_e32 v24, 16, v26
	v_and_b32_e32 v25, 0xffff0000, v26
	v_lshlrev_b32_e32 v26, 16, v27
	v_and_b32_e32 v27, 0xffff0000, v27
	v_pk_fma_f32 v[24:25], v[192:193], v[68:69], v[24:25]
	v_pk_fma_f32 v[26:27], v[194:195], v[70:71], v[26:27]
	v_cvt_pk_bf16_f32 v24, v24, v25
	v_cvt_pk_bf16_f32 v25, v26, v27
	global_store_dwordx2 v177, v[24:25], s[24:25] offset:256
	global_load_dwordx2 v[26:27], v179, s[24:25] offset:256
	s_waitcnt vmcnt(18)
; __device__ __forceinline__ int fresh_tid() { int t = threadIdx.x; asm volatile("" : "+v"(t)); return t; }
; __device__ __forceinline__ unsigned cvt_pk_bf16(float lo, float hi) { unsigned r; asm volatile("v_cvt_pk_bf16_f32 %0, %1, %2" : "=v"(r) : "v"(lo), "v"(hi)); return r; }
;     __device__ __forceinline__ void operator()(const f32x4 (&acc)[2][2][4][2], const Unit& u, int wr, int wc, int fr_, int fq_) const {
;         (void)fr_; (void)fq_; const int l_ = fresh_tid() & 63, fr = l_ & 15, fq = l_ >> 4;
;         const int col0 = u.pn * BM + wc * 32 + 4 * fq;
;         const bool prm = u.pm < MP / BM;
; #pragma unroll
;         for (int ai = 0; ai < 2; ++ai)
; #pragma unroll
;             for (int m = 0; m < 4; ++m) {
;                 const int rl = ai * HALF + wr * 64 + m * 16 + fr, row = u.pm * BM + rl;
;                 const int b = prm ? (u.pm >> 3) : NB_P + (rl >> 5);
;                 const size_t xoff = (prm ? (size_t)row * D : (size_t)(row - MP) * D) + col0;
;                 const float* gr = gate + (size_t)b * NMOD + col0;
;                 bf16_t* orow = out + (size_t)row * D + col0;
; #pragma unroll
;                 for (int bj = 0; bj < 2; ++bj)
; #pragma unroll
;                     for (int n = 0; n < 2; ++n) { f32x4 xv;
;                         if (IN_F32) xv = *(const f32x4*)((const float*)(prm ? xin_p : xin_s) + xoff + bj * HALF + n * 16);
;                         else { const u32x2 w = *(const u32x2*)((const bf16_t*)(prm ? xin_p : xin_s) + xoff + bj * HALF + n * 16); xv = (f32x4){bflo(w.x), bfhi(w.x), bflo(w.y), bfhi(w.y)}; }
;                         const f32x4 gv = *(const f32x4*)(gr + bj * HALF + n * 16);
;                         const f32x4 r = xv + (gv * coef) * acc[ai][bj][m][n];
;                         u32x2 o; o.x = cvt_pk_bf16(r[0], r[1]); o.y = cvt_pk_bf16(r[2], r[3]); *(u32x2*)(orow + bj * HALF + n * 16) = o; }
;                 asm volatile("" ::: "memory"); }
;     }
	v_lshlrev_b32_e32 v28, 16, v30
	v_and_b32_e32 v29, 0xffff0000, v30
	v_lshlrev_b32_e32 v30, 16, v31
	v_and_b32_e32 v31, 0xffff0000, v31
	v_pk_fma_f32 v[28:29], v[196:197], v[56:57], v[28:29]
	v_pk_fma_f32 v[30:31], v[198:199], v[58:59], v[30:31]
	v_cvt_pk_bf16_f32 v28, v28, v29
	v_cvt_pk_bf16_f32 v29, v30, v31
	global_store_dwordx2 v177, v[28:29], s[24:25] offset:288
	global_load_dwordx2 v[30:31], v179, s[24:25] offset:288
	v_add_u32_e32 v176, 0xa0000, v173
	v_add_u32_e32 v177, 0xb0000, v173
	s_waitcnt vmcnt(14)
	v_pk_mul_f32 v[200:201], v[200:201], s[12:13] op_sel_hi:[1,0]
	v_pk_mul_f32 v[202:203], v[202:203], s[12:13] op_sel_hi:[1,0]
	v_pk_mul_f32 v[204:205], v[204:205], s[12:13] op_sel_hi:[1,0]
	v_pk_mul_f32 v[206:207], v[206:207], s[12:13] op_sel_hi:[1,0]
	v_pk_mul_f32 v[212:213], v[212:213], s[12:13] op_sel_hi:[1,0]
	v_pk_mul_f32 v[214:215], v[214:215], s[12:13] op_sel_hi:[1,0]
	v_pk_mul_f32 v[216:217], v[216:217], s[12:13] op_sel_hi:[1,0]
	v_pk_mul_f32 v[218:219], v[218:219], s[12:13] op_sel_hi:[1,0]
	v_lshlrev_b32_e32 v0, 16, v2
	v_and_b32_e32 v1, 0xffff0000, v2
	v_lshlrev_b32_e32 v2, 16, v3
	v_and_b32_e32 v3, 0xffff0000, v3
	v_pk_fma_f32 v[0:1], v[200:201], v[64:65], v[0:1]
	v_pk_fma_f32 v[2:3], v[202:203], v[66:67], v[2:3]
	v_cvt_pk_bf16_f32 v0, v0, v1
	v_cvt_pk_bf16_f32 v1, v2, v3
	global_store_dwordx2 v176, v[0:1], s[24:25]
	s_waitcnt vmcnt(13)
	v_lshlrev_b32_e32 v4, 16, v6
	v_and_b32_e32 v5, 0xffff0000, v6
	v_lshlrev_b32_e32 v6, 16, v7
	v_and_b32_e32 v7, 0xffff0000, v7
	v_pk_fma_f32 v[4:5], v[204:205], v[60:61], v[4:5]
	v_pk_fma_f32 v[6:7], v[206:207], v[62:63], v[6:7]
	v_cvt_pk_bf16_f32 v4, v4, v5
	v_cvt_pk_bf16_f32 v5, v6, v7
	global_store_dwordx2 v176, v[4:5], s[24:25] offset:32
	s_waitcnt vmcnt(12)
	v_lshlrev_b32_e32 v8, 16, v10
	v_and_b32_e32 v9, 0xffff0000, v10
	v_lshlrev_b32_e32 v10, 16, v11
	v_and_b32_e32 v11, 0xffff0000, v11
	v_pk_fma_f32 v[8:9], v[212:213], v[52:53], v[8:9]
	v_pk_fma_f32 v[10:11], v[214:215], v[54:55], v[10:11]
	v_cvt_pk_bf16_f32 v8, v8, v9
	v_cvt_pk_bf16_f32 v9, v10, v11
	global_store_dwordx2 v176, v[8:9], s[24:25] offset:256
	s_waitcnt vmcnt(11)
	v_lshlrev_b32_e32 v12, 16, v14
	v_and_b32_e32 v13, 0xffff0000, v14
	v_lshlrev_b32_e32 v14, 16, v15
	v_and_b32_e32 v15, 0xffff0000, v15
	v_pk_fma_f32 v[12:13], v[216:217], v[40:41], v[12:13]
	v_pk_fma_f32 v[14:15], v[218:219], v[42:43], v[14:15]
	v_cvt_pk_bf16_f32 v12, v12, v13
	v_cvt_pk_bf16_f32 v13, v14, v15
	global_store_dwordx2 v176, v[12:13], s[24:25] offset:288
	s_waitcnt vmcnt(10)
	v_lshlrev_b32_e32 v16, 16, v18
	v_and_b32_e32 v17, 0xffff0000, v18
	v_lshlrev_b32_e32 v18, 16, v19
	v_and_b32_e32 v19, 0xffff0000, v19
	v_pk_fma_f32 v[16:17], v[200:201], v[48:49], v[16:17]
	v_pk_fma_f32 v[18:19], v[202:203], v[50:51], v[18:19]
	v_cvt_pk_bf16_f32 v16, v16, v17
	v_cvt_pk_bf16_f32 v17, v18, v19
	global_store_dwordx2 v177, v[16:17], s[24:25]
	s_waitcnt vmcnt(9)
	v_lshlrev_b32_e32 v20, 16, v22
	v_and_b32_e32 v21, 0xffff0000, v22
	v_lshlrev_b32_e32 v22, 16, v23
	v_and_b32_e32 v23, 0xffff0000, v23
	v_pk_fma_f32 v[20:21], v[204:205], v[44:45], v[20:21]
	v_pk_fma_f32 v[22:23], v[206:207], v[46:47], v[22:23]
	v_cvt_pk_bf16_f32 v20, v20, v21
	v_cvt_pk_bf16_f32 v21, v22, v23
	global_store_dwordx2 v177, v[20:21], s[24:25] offset:32
	s_waitcnt vmcnt(8)
	v_lshlrev_b32_e32 v24, 16, v26
	v_and_b32_e32 v25, 0xffff0000, v26
	v_lshlrev_b32_e32 v26, 16, v27
	v_and_b32_e32 v27, 0xffff0000, v27
	v_pk_fma_f32 v[24:25], v[212:213], v[36:37], v[24:25]
	v_pk_fma_f32 v[26:27], v[214:215], v[38:39], v[26:27]
	v_cvt_pk_bf16_f32 v24, v24, v25
	v_cvt_pk_bf16_f32 v25, v26, v27
	global_store_dwordx2 v177, v[24:25], s[24:25] offset:256
	s_waitcnt vmcnt(7)
	v_lshlrev_b32_e32 v28, 16, v30
	v_and_b32_e32 v29, 0xffff0000, v30
	v_lshlrev_b32_e32 v30, 16, v31
	v_and_b32_e32 v31, 0xffff0000, v31
	v_pk_fma_f32 v[28:29], v[216:217], v[32:33], v[28:29]
	v_pk_fma_f32 v[30:31], v[218:219], v[34:35], v[30:31]
	v_cvt_pk_bf16_f32 v28, v28, v29
	v_cvt_pk_bf16_f32 v29, v30, v31
	global_store_dwordx2 v177, v[28:29], s[24:25] offset:288
